# sg outputs stored as dwords (neighbour lanes paired through DPP) instead of 64 two-byte stores per lane, on the non-GEMM latency stack
# baseline (speedup 1.0000x reference)
; __device__ __forceinline__ void sg_item(int l, int chunk, LAS unsigned char* lds, const bf16_t* UB, const bf16_t* V2T, bf16_t* YC1, const bf16_t* Wb,
;                                         const float* sg_ln_g, const float* sg_ln_b, const float* sg_b, int lane, int wave) {
;     ...
;         const int th = wave & 1, cq = wave >> 1, s = 64 * th + lane;
;         const bf16_t* src = V2T + ((size_t)b * BW + 64 * cq) * SEQ + pos0;
;         float v[64]; float sum = 0.f, sq = 0.f;
; #pragma unroll
;         for (int cb = 0; cb < 64; cb += 8) {
;             unsigned raw[8]; const void* pp[8];
; #pragma unroll
;             for (int j = 0; j < 8; ++j) pp[j] = src + (size_t)(cb + j) * SEQ;
;             ld_u16_s8(raw, (unsigned)s * 2u, pp);
; #pragma unroll
;             for (int j = 0; j < 8; ++j) v[cb + j] = __uint_as_float(raw[j] << 16);
;         }
.LBB0_79:
	s_and_b32 s12, s88, 0xf80
	s_and_b32 s1, s85, 0x7ffff
	s_and_b32 s0, s84, 0xffffff00
	s_add_u32 s0, s0, s15
	s_addc_u32 s1, s1, s46
	s_lshl_b64 s[0:1], s[0:1], 13
	s_add_u32 s0, s2, s0
	s_addc_u32 s1, s3, s1
	s_lshl_b32 s12, s12, 1
	s_add_u32 s0, s0, s12
	s_addc_u32 s1, s1, 0
	s_mov_b64 s[48:49], s[0:1]
	s_nop 4
	global_load_ushort v132, v149, s[48:49]
	s_add_u32 s48, s48, 0x2000
	s_addc_u32 s49, s49, 0
	global_load_ushort v133, v149, s[48:49]
	s_add_u32 s48, s48, 0x2000
	s_addc_u32 s49, s49, 0
	global_load_ushort v130, v149, s[48:49]
	s_add_u32 s48, s48, 0x2000
	s_addc_u32 s49, s49, 0
	global_load_ushort v128, v149, s[48:49]
	s_add_u32 s48, s48, 0x2000
	s_addc_u32 s49, s49, 0
	global_load_ushort v126, v149, s[48:49]
	s_add_u32 s48, s48, 0x2000
	s_addc_u32 s49, s49, 0
	global_load_ushort v124, v149, s[48:49]
	s_add_u32 s48, s48, 0x2000
	s_addc_u32 s49, s49, 0
	global_load_ushort v120, v149, s[48:49]
	s_add_u32 s48, s48, 0x2000
	s_addc_u32 s49, s49, 0
	global_load_ushort v116, v149, s[48:49]
	s_add_u32 s48, s48, 0x2000
	s_addc_u32 s49, s49, 0
	global_load_ushort v122, v149, s[48:49]
	s_add_u32 s48, s48, 0x2000
	s_addc_u32 s49, s49, 0
	global_load_ushort v118, v149, s[48:49]
	s_add_u32 s48, s48, 0x2000
	s_addc_u32 s49, s49, 0
	global_load_ushort v114, v149, s[48:49]
	s_add_u32 s48, s48, 0x2000
	s_addc_u32 s49, s49, 0
	global_load_ushort v112, v149, s[48:49]
	s_add_u32 s48, s48, 0x2000
	s_addc_u32 s49, s49, 0
	global_load_ushort v110, v149, s[48:49]
	s_add_u32 s48, s48, 0x2000
	s_addc_u32 s49, s49, 0
	global_load_ushort v108, v149, s[48:49]
	s_add_u32 s48, s48, 0x2000
	s_addc_u32 s49, s49, 0
	global_load_ushort v104, v149, s[48:49]
	s_add_u32 s48, s48, 0x2000
	s_addc_u32 s49, s49, 0
	global_load_ushort v100, v149, s[48:49]
	s_add_u32 s48, s48, 0x2000
	s_addc_u32 s49, s49, 0
	global_load_ushort v106, v149, s[48:49]
	s_add_u32 s48, s48, 0x2000
	s_addc_u32 s49, s49, 0
	global_load_ushort v102, v149, s[48:49]
	s_add_u32 s48, s48, 0x2000
	s_addc_u32 s49, s49, 0
	global_load_ushort v98, v149, s[48:49]
	s_add_u32 s48, s48, 0x2000
	s_addc_u32 s49, s49, 0
	global_load_ushort v96, v149, s[48:49]
	s_add_u32 s48, s48, 0x2000
	s_addc_u32 s49, s49, 0
	global_load_ushort v94, v149, s[48:49]
	s_add_u32 s48, s48, 0x2000
	s_addc_u32 s49, s49, 0
	global_load_ushort v92, v149, s[48:49]
	s_add_u32 s48, s48, 0x2000
	s_addc_u32 s49, s49, 0
	global_load_ushort v88, v149, s[48:49]
	s_add_u32 s48, s48, 0x2000
	s_addc_u32 s49, s49, 0
	global_load_ushort v84, v149, s[48:49]
	s_add_u32 s48, s48, 0x2000
	s_addc_u32 s49, s49, 0
	global_load_ushort v90, v149, s[48:49]
	s_add_u32 s48, s48, 0x2000
	s_addc_u32 s49, s49, 0
	global_load_ushort v86, v149, s[48:49]
	s_add_u32 s48, s48, 0x2000
	s_addc_u32 s49, s49, 0
	global_load_ushort v82, v149, s[48:49]
	s_add_u32 s48, s48, 0x2000
	s_addc_u32 s49, s49, 0
	global_load_ushort v80, v149, s[48:49]
	s_add_u32 s48, s48, 0x2000
	s_addc_u32 s49, s49, 0
	global_load_ushort v78, v149, s[48:49]
	s_add_u32 s48, s48, 0x2000
	s_addc_u32 s49, s49, 0
	global_load_ushort v76, v149, s[48:49]
	s_add_u32 s48, s48, 0x2000
	s_addc_u32 s49, s49, 0
	global_load_ushort v72, v149, s[48:49]
	s_add_u32 s48, s48, 0x2000
	s_addc_u32 s49, s49, 0
	global_load_ushort v60, v149, s[48:49]
	s_add_u32 s48, s48, 0x2000
	s_addc_u32 s49, s49, 0
	global_load_ushort v74, v149, s[48:49]
	s_add_u32 s48, s48, 0x2000
	s_addc_u32 s49, s49, 0
	global_load_ushort v62, v149, s[48:49]
	s_add_u32 s48, s48, 0x2000
	s_addc_u32 s49, s49, 0
	global_load_ushort v58, v149, s[48:49]
	s_add_u32 s48, s48, 0x2000
	s_addc_u32 s49, s49, 0
	global_load_ushort v56, v149, s[48:49]
	s_add_u32 s48, s48, 0x2000
	s_addc_u32 s49, s49, 0
	global_load_ushort v54, v149, s[48:49]
	s_add_u32 s48, s48, 0x2000
	s_addc_u32 s49, s49, 0
	global_load_ushort v52, v149, s[48:49]
	s_add_u32 s48, s48, 0x2000
	s_addc_u32 s49, s49, 0
	global_load_ushort v48, v149, s[48:49]
	s_add_u32 s48, s48, 0x2000
	s_addc_u32 s49, s49, 0
	global_load_ushort v44, v149, s[48:49]
	s_add_u32 s48, s48, 0x2000
	s_addc_u32 s49, s49, 0
	global_load_ushort v50, v149, s[48:49]
	s_add_u32 s48, s48, 0x2000
	s_addc_u32 s49, s49, 0
	global_load_ushort v46, v149, s[48:49]
	s_add_u32 s48, s48, 0x2000
	s_addc_u32 s49, s49, 0
	global_load_ushort v42, v149, s[48:49]
	s_add_u32 s48, s48, 0x2000
	s_addc_u32 s49, s49, 0
	global_load_ushort v40, v149, s[48:49]
	s_add_u32 s48, s48, 0x2000
	s_addc_u32 s49, s49, 0
	global_load_ushort v38, v149, s[48:49]
	s_add_u32 s48, s48, 0x2000
	s_addc_u32 s49, s49, 0
	global_load_ushort v36, v149, s[48:49]
	s_add_u32 s48, s48, 0x2000
	s_addc_u32 s49, s49, 0
	global_load_ushort v32, v149, s[48:49]
	s_add_u32 s48, s48, 0x2000
	s_addc_u32 s49, s49, 0
	global_load_ushort v28, v149, s[48:49]
	s_add_u32 s48, s48, 0x2000
	s_addc_u32 s49, s49, 0
	global_load_ushort v34, v149, s[48:49]
	s_add_u32 s48, s48, 0x2000
	s_addc_u32 s49, s49, 0
	global_load_ushort v30, v149, s[48:49]
	s_add_u32 s48, s48, 0x2000
	s_addc_u32 s49, s49, 0
	global_load_ushort v26, v149, s[48:49]
	s_add_u32 s48, s48, 0x2000
	s_addc_u32 s49, s49, 0
	global_load_ushort v24, v149, s[48:49]
	s_add_u32 s48, s48, 0x2000
	s_addc_u32 s49, s49, 0
	global_load_ushort v22, v149, s[48:49]
	s_add_u32 s48, s48, 0x2000
	s_addc_u32 s49, s49, 0
	global_load_ushort v20, v149, s[48:49]
	s_add_u32 s48, s48, 0x2000
	s_addc_u32 s49, s49, 0
	global_load_ushort v16, v149, s[48:49]
	s_add_u32 s48, s48, 0x2000
	s_addc_u32 s49, s49, 0
	global_load_ushort v12, v149, s[48:49]
	s_add_u32 s48, s48, 0x2000
	s_addc_u32 s49, s49, 0
	global_load_ushort v18, v149, s[48:49]
	s_add_u32 s48, s48, 0x2000
	s_addc_u32 s49, s49, 0
	global_load_ushort v14, v149, s[48:49]
	s_add_u32 s48, s48, 0x2000
	s_addc_u32 s49, s49, 0
	global_load_ushort v10, v149, s[48:49]
	s_add_u32 s48, s48, 0x2000
	s_addc_u32 s49, s49, 0
	global_load_ushort v8, v149, s[48:49]
	s_add_u32 s48, s48, 0x2000
	s_addc_u32 s49, s49, 0
	global_load_ushort v6, v149, s[48:49]
	s_add_u32 s48, s48, 0x2000
	s_addc_u32 s49, s49, 0
	global_load_ushort v4, v149, s[48:49]
	s_add_u32 s48, s48, 0x2000
	s_addc_u32 s49, s49, 0
	global_load_ushort v2, v149, s[48:49]
	s_add_u32 s48, s48, 0x2000
	s_addc_u32 s49, s49, 0
	global_load_ushort v0, v149, s[48:49]
	s_waitcnt vmcnt(0)
; __device__ __forceinline__ void sg_item(int l, int chunk, LAS unsigned char* lds, const bf16_t* UB, const bf16_t* V2T, bf16_t* YC1, const bf16_t* Wb,
;                                         const float* sg_ln_g, const float* sg_ln_b, const float* sg_b, int lane, int wave) {
;     ...
;         const int th = wave & 1, cq = wave >> 1, s = 64 * th + lane;
;         const bf16_t* src = V2T + ((size_t)b * BW + 64 * cq) * SEQ + pos0;
;         float v[64]; float sum = 0.f, sq = 0.f;
; #pragma unroll
;         for (int cb = 0; cb < 64; cb += 8) {
;             unsigned raw[8]; const void* pp[8];
; #pragma unroll
;             for (int j = 0; j < 8; ++j) pp[j] = src + (size_t)(cb + j) * SEQ;
;             ld_u16_s8(raw, (unsigned)s * 2u, pp);
; #pragma unroll
;             for (int j = 0; j < 8; ++j) v[cb + j] = __uint_as_float(raw[j] << 16);
;         }
; #pragma unroll
;         for (int c = 0; c < 64; ++c) { sum += v[c]; sq += v[c] * v[c]; }
	v_lshlrev_b32_e32 v132, 16, v132
	v_lshlrev_b32_e32 v133, 16, v133
	v_lshlrev_b32_e32 v130, 16, v130
	v_lshlrev_b32_e32 v128, 16, v128
	v_lshlrev_b32_e32 v126, 16, v126
	v_lshlrev_b32_e32 v124, 16, v124
	v_lshlrev_b32_e32 v120, 16, v120
	v_lshlrev_b32_e32 v116, 16, v116
	v_lshlrev_b32_e32 v122, 16, v122
	v_lshlrev_b32_e32 v118, 16, v118
	v_lshlrev_b32_e32 v114, 16, v114
	v_lshlrev_b32_e32 v112, 16, v112
	v_lshlrev_b32_e32 v110, 16, v110
	v_lshlrev_b32_e32 v108, 16, v108
	v_lshlrev_b32_e32 v104, 16, v104
	v_lshlrev_b32_e32 v100, 16, v100
	v_lshlrev_b32_e32 v106, 16, v106
	v_lshlrev_b32_e32 v102, 16, v102
	v_lshlrev_b32_e32 v98, 16, v98
	v_lshlrev_b32_e32 v96, 16, v96
	v_lshlrev_b32_e32 v94, 16, v94
	v_lshlrev_b32_e32 v92, 16, v92
	v_lshlrev_b32_e32 v88, 16, v88
	v_lshlrev_b32_e32 v84, 16, v84
	v_lshlrev_b32_e32 v90, 16, v90
	v_lshlrev_b32_e32 v86, 16, v86
	v_lshlrev_b32_e32 v82, 16, v82
	v_lshlrev_b32_e32 v80, 16, v80
	v_lshlrev_b32_e32 v78, 16, v78
	v_lshlrev_b32_e32 v76, 16, v76
	v_lshlrev_b32_e32 v72, 16, v72
	v_lshlrev_b32_e32 v60, 16, v60
	v_lshlrev_b32_e32 v74, 16, v74
	v_lshlrev_b32_e32 v62, 16, v62
	v_lshlrev_b32_e32 v58, 16, v58
	v_lshlrev_b32_e32 v56, 16, v56
	v_lshlrev_b32_e32 v54, 16, v54
	v_lshlrev_b32_e32 v52, 16, v52
	v_lshlrev_b32_e32 v48, 16, v48
	v_lshlrev_b32_e32 v44, 16, v44
	v_lshlrev_b32_e32 v50, 16, v50
	v_lshlrev_b32_e32 v46, 16, v46
	v_lshlrev_b32_e32 v42, 16, v42
	v_lshlrev_b32_e32 v40, 16, v40
	v_lshlrev_b32_e32 v38, 16, v38
	v_lshlrev_b32_e32 v36, 16, v36
	v_lshlrev_b32_e32 v32, 16, v32
	v_lshlrev_b32_e32 v28, 16, v28
	v_lshlrev_b32_e32 v34, 16, v34
	v_lshlrev_b32_e32 v30, 16, v30
	v_lshlrev_b32_e32 v26, 16, v26
	v_lshlrev_b32_e32 v24, 16, v24
	v_lshlrev_b32_e32 v22, 16, v22
	v_lshlrev_b32_e32 v20, 16, v20
	v_lshlrev_b32_e32 v16, 16, v16
	v_lshlrev_b32_e32 v12, 16, v12
	v_lshlrev_b32_e32 v18, 16, v18
	v_lshlrev_b32_e32 v14, 16, v14
	v_lshlrev_b32_e32 v10, 16, v10
	v_lshlrev_b32_e32 v8, 16, v8
	v_lshlrev_b32_e32 v6, 16, v6
	v_lshlrev_b32_e32 v4, 16, v4
	v_lshlrev_b32_e32 v2, 16, v2
	v_lshlrev_b32_e32 v0, 16, v0
	v_mul_f32_e32 v221, v132, v132
	v_fmac_f32_e32 v221, v133, v133
	v_add_f32_e32 v220, v132, v133
	v_mul_f32_e32 v131, v130, v130
	v_pk_add_f32 v[220:221], v[220:221], v[130:131]
	v_mul_f32_e32 v129, v128, v128
	v_pk_add_f32 v[220:221], v[220:221], v[128:129]
	v_mul_f32_e32 v127, v126, v126
	v_pk_add_f32 v[220:221], v[220:221], v[126:127]
	v_mul_f32_e32 v125, v124, v124
	v_pk_add_f32 v[220:221], v[220:221], v[124:125]
	v_mul_f32_e32 v121, v120, v120
	v_pk_add_f32 v[220:221], v[220:221], v[120:121]
	v_mul_f32_e32 v117, v116, v116
	v_pk_add_f32 v[220:221], v[220:221], v[116:117]
	v_mul_f32_e32 v123, v122, v122
	v_pk_add_f32 v[220:221], v[220:221], v[122:123]
	v_mul_f32_e32 v119, v118, v118
	v_pk_add_f32 v[220:221], v[220:221], v[118:119]
	v_mul_f32_e32 v115, v114, v114
	v_pk_add_f32 v[220:221], v[220:221], v[114:115]
	v_mul_f32_e32 v113, v112, v112
	v_pk_add_f32 v[220:221], v[220:221], v[112:113]
	v_mul_f32_e32 v111, v110, v110
	v_pk_add_f32 v[220:221], v[220:221], v[110:111]
	v_mul_f32_e32 v109, v108, v108
	v_pk_add_f32 v[220:221], v[220:221], v[108:109]
	v_mul_f32_e32 v105, v104, v104
	v_pk_add_f32 v[220:221], v[220:221], v[104:105]
	v_mul_f32_e32 v101, v100, v100
	v_pk_add_f32 v[220:221], v[220:221], v[100:101]
	v_mul_f32_e32 v107, v106, v106
	v_pk_add_f32 v[220:221], v[220:221], v[106:107]
	v_mul_f32_e32 v103, v102, v102
	v_pk_add_f32 v[220:221], v[220:221], v[102:103]
	v_mul_f32_e32 v99, v98, v98
	v_pk_add_f32 v[220:221], v[220:221], v[98:99]
	v_mul_f32_e32 v97, v96, v96
	v_pk_add_f32 v[220:221], v[220:221], v[96:97]
	v_mul_f32_e32 v95, v94, v94
	v_pk_add_f32 v[220:221], v[220:221], v[94:95]
	v_mul_f32_e32 v93, v92, v92
	v_pk_add_f32 v[220:221], v[220:221], v[92:93]
	v_mul_f32_e32 v89, v88, v88
	v_pk_add_f32 v[220:221], v[220:221], v[88:89]
	v_mul_f32_e32 v85, v84, v84
	v_pk_add_f32 v[220:221], v[220:221], v[84:85]
	v_mul_f32_e32 v91, v90, v90
	v_pk_add_f32 v[220:221], v[220:221], v[90:91]
	v_mul_f32_e32 v87, v86, v86
	v_pk_add_f32 v[220:221], v[220:221], v[86:87]
	v_mul_f32_e32 v83, v82, v82
	v_pk_add_f32 v[220:221], v[220:221], v[82:83]
	v_mul_f32_e32 v81, v80, v80
	v_pk_add_f32 v[220:221], v[220:221], v[80:81]
	v_mul_f32_e32 v79, v78, v78
	v_pk_add_f32 v[220:221], v[220:221], v[78:79]
	v_mul_f32_e32 v77, v76, v76
	v_pk_add_f32 v[220:221], v[220:221], v[76:77]
	v_mul_f32_e32 v73, v72, v72
	v_pk_add_f32 v[220:221], v[220:221], v[72:73]
	v_mul_f32_e32 v61, v60, v60
	v_pk_add_f32 v[220:221], v[220:221], v[60:61]
	v_mul_f32_e32 v75, v74, v74
	v_pk_add_f32 v[220:221], v[220:221], v[74:75]
	v_mul_f32_e32 v63, v62, v62
	v_pk_add_f32 v[220:221], v[220:221], v[62:63]
	v_mul_f32_e32 v59, v58, v58
	v_pk_add_f32 v[220:221], v[220:221], v[58:59]
	v_mul_f32_e32 v57, v56, v56
	v_pk_add_f32 v[220:221], v[220:221], v[56:57]
	v_mul_f32_e32 v55, v54, v54
	v_pk_add_f32 v[220:221], v[220:221], v[54:55]
	v_mul_f32_e32 v53, v52, v52
	v_pk_add_f32 v[220:221], v[220:221], v[52:53]
	v_mul_f32_e32 v49, v48, v48
	v_pk_add_f32 v[220:221], v[220:221], v[48:49]
	v_mul_f32_e32 v45, v44, v44
	v_pk_add_f32 v[220:221], v[220:221], v[44:45]
	v_mul_f32_e32 v51, v50, v50
	v_pk_add_f32 v[220:221], v[220:221], v[50:51]
	v_mul_f32_e32 v47, v46, v46
	v_pk_add_f32 v[220:221], v[220:221], v[46:47]
	v_mul_f32_e32 v43, v42, v42
	v_pk_add_f32 v[220:221], v[220:221], v[42:43]
	v_mul_f32_e32 v41, v40, v40
	v_pk_add_f32 v[220:221], v[220:221], v[40:41]
	v_mul_f32_e32 v39, v38, v38
	v_pk_add_f32 v[220:221], v[220:221], v[38:39]
	v_mul_f32_e32 v37, v36, v36
	v_pk_add_f32 v[220:221], v[220:221], v[36:37]
	v_mul_f32_e32 v33, v32, v32
; __device__ __forceinline__ bf16_t f2bf(float f) { return (bf16_t)(cvt_pk_bf16(f, f) & 0xffffu); }
; __device__ __forceinline__ float ln_eps_s() { float e = LN_EPS; asm volatile("" : "+s"(e)); return e; }
; __device__ __forceinline__ void sg_item(int l, int chunk, LAS unsigned char* lds, const bf16_t* UB, const bf16_t* V2T, bf16_t* YC1, const bf16_t* Wb,
;                                         const float* sg_ln_g, const float* sg_ln_b, const float* sg_b, int lane, int wave) {
;     ...
;         for (int c = 0; c < 64; ++c) { sum += v[c]; sq += v[c] * v[c]; }
;         part[(cq * 128 + s) * 2] = sum; part[(cq * 128 + s) * 2 + 1] = sq;
;         const float gl = sg_ln_g[l * BW + 64 * cq + lane], bl = sg_ln_b[l * BW + 64 * cq + lane];
;         __syncthreads();
;         float ts = 0.f, tq = 0.f;
; #pragma unroll
;         for (int k = 0; k < 4; ++k) { ts += part[(k * 128 + s) * 2]; tq += part[(k * 128 + s) * 2 + 1]; }
;         const float mean = ts * (1.f / BW), var = fmaxf(tq * (1.f / BW) - mean * mean, 0.f), rstd = __builtin_amdgcn_rsqf(var + ln_eps_s());
; #pragma unroll
;         for (int c = 0; c < 64; ++c) {
;             const float gc = __uint_as_float(__builtin_amdgcn_readlane(__float_as_uint(gl), c)), bc = __uint_as_float(__builtin_amdgcn_readlane(__float_as_uint(bl), c));
;             vT[(64 * cq + c) * VS + s] = f2bf((v[c] - mean) * rstd * gc + bc);
	v_pk_add_f32 v[220:221], v[220:221], v[32:33]
	v_mul_f32_e32 v29, v28, v28
	v_pk_add_f32 v[220:221], v[220:221], v[28:29]
	v_mul_f32_e32 v35, v34, v34
	v_pk_add_f32 v[220:221], v[220:221], v[34:35]
	v_mul_f32_e32 v31, v30, v30
	v_pk_add_f32 v[220:221], v[220:221], v[30:31]
	v_mul_f32_e32 v27, v26, v26
	v_pk_add_f32 v[220:221], v[220:221], v[26:27]
	v_mul_f32_e32 v25, v24, v24
	v_pk_add_f32 v[220:221], v[220:221], v[24:25]
	v_mul_f32_e32 v23, v22, v22
	v_pk_add_f32 v[220:221], v[220:221], v[22:23]
	v_mul_f32_e32 v21, v20, v20
	v_pk_add_f32 v[220:221], v[220:221], v[20:21]
	v_mul_f32_e32 v17, v16, v16
	v_pk_add_f32 v[220:221], v[220:221], v[16:17]
	v_mul_f32_e32 v13, v12, v12
	v_pk_add_f32 v[220:221], v[220:221], v[12:13]
	v_mul_f32_e32 v19, v18, v18
	v_pk_add_f32 v[220:221], v[220:221], v[18:19]
	v_mul_f32_e32 v15, v14, v14
	v_pk_add_f32 v[220:221], v[220:221], v[14:15]
	v_mul_f32_e32 v11, v10, v10
	v_pk_add_f32 v[220:221], v[220:221], v[10:11]
	v_mul_f32_e32 v9, v8, v8
	v_pk_add_f32 v[220:221], v[220:221], v[8:9]
	v_mul_f32_e32 v7, v6, v6
	v_pk_add_f32 v[220:221], v[220:221], v[6:7]
	v_mul_f32_e32 v5, v4, v4
	v_pk_add_f32 v[220:221], v[220:221], v[4:5]
	v_mul_f32_e32 v3, v2, v2
	v_pk_add_f32 v[220:221], v[220:221], v[2:3]
	v_mul_f32_e32 v1, v0, v0
	v_pk_add_f32 v[220:221], v[220:221], v[0:1]
	s_mov_b32 s0, 0x3b800000
	ds_write_b64 v150, v[220:221]
	global_load_dword v1, v[64:65], off
	global_load_dword v3, v[66:67], off
	s_waitcnt lgkmcnt(0)
	s_barrier
	ds_read2st64_b64 v[220:223], v151 offset1:2
	s_add_u32 s48, s4, s80
	s_addc_u32 s49, s5, s81
	s_mov_b32 s12, 0xb400000
	s_waitcnt lgkmcnt(0)
	v_add_f32_e32 v5, 0, v220
	v_add_f32_e32 v7, 0, v221
	v_add_f32_e32 v5, v5, v222
	v_add_f32_e32 v7, v7, v223
	ds_read2st64_b64 v[220:223], v151 offset0:4 offset1:6
	s_waitcnt lgkmcnt(0)
	v_add_f32_e32 v5, v5, v220
	v_add_f32_e32 v5, v5, v222
	v_add_f32_e32 v7, v7, v221
	v_mul_f32_e32 v9, 0x3b800000, v5
	v_add_f32_e32 v7, v7, v223
	v_mul_f32_e32 v9, v9, v9
	v_fma_f32 v7, v7, s0, -v9
	v_max_f32_e32 v7, 0, v7
	s_mov_b32 s0, 0x3727c5ac
	v_fmac_f32_e32 v132, 0xbb800000, v5
	v_add_f32_e32 v7, s0, v7
	v_rsq_f32_e32 v7, v7
	v_fmac_f32_e32 v133, 0xbb800000, v5
	v_fmac_f32_e32 v130, 0xbb800000, v5
	v_fmac_f32_e32 v128, 0xbb800000, v5
	v_mul_f32_e32 v9, v132, v7
	v_fmac_f32_e32 v126, 0xbb800000, v5
	v_fmac_f32_e32 v124, 0xbb800000, v5
	v_fmac_f32_e32 v120, 0xbb800000, v5
	v_fmac_f32_e32 v116, 0xbb800000, v5
	v_fmac_f32_e32 v122, 0xbb800000, v5
	v_fmac_f32_e32 v118, 0xbb800000, v5
	v_fmac_f32_e32 v114, 0xbb800000, v5
	v_fmac_f32_e32 v112, 0xbb800000, v5
	v_fmac_f32_e32 v110, 0xbb800000, v5
	v_fmac_f32_e32 v108, 0xbb800000, v5
	v_fmac_f32_e32 v104, 0xbb800000, v5
	v_fmac_f32_e32 v100, 0xbb800000, v5
	v_fmac_f32_e32 v106, 0xbb800000, v5
	v_fmac_f32_e32 v102, 0xbb800000, v5
	v_fmac_f32_e32 v98, 0xbb800000, v5
	v_fmac_f32_e32 v96, 0xbb800000, v5
	v_fmac_f32_e32 v94, 0xbb800000, v5
	v_fmac_f32_e32 v92, 0xbb800000, v5
	v_fmac_f32_e32 v88, 0xbb800000, v5
	v_fmac_f32_e32 v84, 0xbb800000, v5
	v_fmac_f32_e32 v90, 0xbb800000, v5
	v_fmac_f32_e32 v86, 0xbb800000, v5
	v_fmac_f32_e32 v82, 0xbb800000, v5
	v_fmac_f32_e32 v80, 0xbb800000, v5
	v_fmac_f32_e32 v78, 0xbb800000, v5
	v_fmac_f32_e32 v76, 0xbb800000, v5
	v_fmac_f32_e32 v72, 0xbb800000, v5
	v_fmac_f32_e32 v60, 0xbb800000, v5
	v_fmac_f32_e32 v74, 0xbb800000, v5
	v_fmac_f32_e32 v62, 0xbb800000, v5
	v_fmac_f32_e32 v58, 0xbb800000, v5
	v_fmac_f32_e32 v56, 0xbb800000, v5
	v_fmac_f32_e32 v54, 0xbb800000, v5
	v_fmac_f32_e32 v52, 0xbb800000, v5
	v_fmac_f32_e32 v48, 0xbb800000, v5
	v_fmac_f32_e32 v44, 0xbb800000, v5
	v_fmac_f32_e32 v50, 0xbb800000, v5
	v_fmac_f32_e32 v46, 0xbb800000, v5
	v_fmac_f32_e32 v42, 0xbb800000, v5
	v_fmac_f32_e32 v40, 0xbb800000, v5
	v_fmac_f32_e32 v38, 0xbb800000, v5
	v_fmac_f32_e32 v36, 0xbb800000, v5
	v_fmac_f32_e32 v32, 0xbb800000, v5
	v_fmac_f32_e32 v28, 0xbb800000, v5
	s_waitcnt vmcnt(1)
	v_readlane_b32 s0, v1, 0
	s_waitcnt vmcnt(0)
	v_readlane_b32 s1, v3, 0
	v_fmac_f32_e32 v34, 0xbb800000, v5
	v_fmac_f32_e32 v30, 0xbb800000, v5
	v_mov_b32_e32 v11, s1
	v_fmac_f32_e32 v11, s0, v9
	v_cvt_pk_bf16_f32 v9, v11, v11
	v_readlane_b32 s1, v3, 1
	ds_write_b16 v202, v9
	v_readlane_b32 s0, v1, 1
	v_mul_f32_e32 v9, v133, v7
	v_mov_b32_e32 v11, s1
	v_fmac_f32_e32 v11, s0, v9
	v_cvt_pk_bf16_f32 v9, v11, v11
	v_readlane_b32 s1, v3, 2
	ds_write_b16 v202, v9 offset:272
	v_readlane_b32 s0, v1, 2
	v_mul_f32_e32 v9, v130, v7
	v_mov_b32_e32 v11, s1
	v_fmac_f32_e32 v11, s0, v9
	v_cvt_pk_bf16_f32 v9, v11, v11
	v_readlane_b32 s1, v3, 3
	ds_write_b16 v202, v9 offset:544
	v_readlane_b32 s0, v1, 3
	v_mul_f32_e32 v9, v128, v7
	v_mov_b32_e32 v11, s1
	v_fmac_f32_e32 v11, s0, v9
	v_cvt_pk_bf16_f32 v9, v11, v11
	v_readlane_b32 s1, v3, 4
	ds_write_b16 v202, v9 offset:816
	v_readlane_b32 s0, v1, 4
	v_mul_f32_e32 v9, v126, v7
	v_mov_b32_e32 v11, s1
	v_fmac_f32_e32 v11, s0, v9
	v_cvt_pk_bf16_f32 v9, v11, v11
	v_readlane_b32 s1, v3, 5
	ds_write_b16 v202, v9 offset:1088
	v_readlane_b32 s0, v1, 5
	v_mul_f32_e32 v9, v124, v7
	v_mov_b32_e32 v11, s1
	v_fmac_f32_e32 v11, s0, v9
	v_cvt_pk_bf16_f32 v9, v11, v11
	v_readlane_b32 s1, v3, 6
	ds_write_b16 v202, v9 offset:1360
	v_readlane_b32 s0, v1, 6
	v_mul_f32_e32 v9, v120, v7
	v_mov_b32_e32 v11, s1
	v_fmac_f32_e32 v11, s0, v9
	v_cvt_pk_bf16_f32 v9, v11, v11
	v_readlane_b32 s1, v3, 7
	ds_write_b16 v202, v9 offset:1632
	v_readlane_b32 s0, v1, 7
	v_mul_f32_e32 v9, v116, v7
	v_mov_b32_e32 v11, s1
	v_fmac_f32_e32 v11, s0, v9
	v_cvt_pk_bf16_f32 v9, v11, v11
	v_readlane_b32 s1, v3, 8
	ds_write_b16 v202, v9 offset:1904
	v_readlane_b32 s0, v1, 8
	v_mul_f32_e32 v9, v122, v7
	v_mov_b32_e32 v11, s1
; __device__ __forceinline__ bf16_t f2bf(float f) { return (bf16_t)(cvt_pk_bf16(f, f) & 0xffffu); }
; __device__ __forceinline__ void sg_item(int l, int chunk, LAS unsigned char* lds, const bf16_t* UB, const bf16_t* V2T, bf16_t* YC1, const bf16_t* Wb,
;                                         const float* sg_ln_g, const float* sg_ln_b, const float* sg_b, int lane, int wave) {
;     ...
;         for (int c = 0; c < 64; ++c) {
;             const float gc = __uint_as_float(__builtin_amdgcn_readlane(__float_as_uint(gl), c)), bc = __uint_as_float(__builtin_amdgcn_readlane(__float_as_uint(bl), c));
;             vT[(64 * cq + c) * VS + s] = f2bf((v[c] - mean) * rstd * gc + bc);
;         }
	v_fmac_f32_e32 v11, s0, v9
	v_cvt_pk_bf16_f32 v9, v11, v11
	v_readlane_b32 s1, v3, 9
	ds_write_b16 v202, v9 offset:2176
	v_readlane_b32 s0, v1, 9
	v_mul_f32_e32 v9, v118, v7
	v_mov_b32_e32 v11, s1
	v_fmac_f32_e32 v11, s0, v9
	v_cvt_pk_bf16_f32 v9, v11, v11
	v_readlane_b32 s1, v3, 10
	ds_write_b16 v202, v9 offset:2448
	v_readlane_b32 s0, v1, 10
	v_mul_f32_e32 v9, v114, v7
	v_mov_b32_e32 v11, s1
	v_fmac_f32_e32 v11, s0, v9
	v_cvt_pk_bf16_f32 v9, v11, v11
	v_readlane_b32 s1, v3, 11
	ds_write_b16 v202, v9 offset:2720
	v_readlane_b32 s0, v1, 11
	v_mul_f32_e32 v9, v112, v7
	v_mov_b32_e32 v11, s1
	v_fmac_f32_e32 v11, s0, v9
	v_cvt_pk_bf16_f32 v9, v11, v11
	v_readlane_b32 s1, v3, 12
	ds_write_b16 v202, v9 offset:2992
	v_readlane_b32 s0, v1, 12
	v_mul_f32_e32 v9, v110, v7
	v_mov_b32_e32 v11, s1
	v_fmac_f32_e32 v11, s0, v9
	v_cvt_pk_bf16_f32 v9, v11, v11
	v_readlane_b32 s1, v3, 13
	ds_write_b16 v202, v9 offset:3264
	v_readlane_b32 s0, v1, 13
	v_mul_f32_e32 v9, v108, v7
	v_mov_b32_e32 v11, s1
	v_fmac_f32_e32 v11, s0, v9
	v_cvt_pk_bf16_f32 v9, v11, v11
	v_readlane_b32 s1, v3, 14
	ds_write_b16 v202, v9 offset:3536
	v_readlane_b32 s0, v1, 14
	v_mul_f32_e32 v9, v104, v7
	v_mov_b32_e32 v11, s1
	v_fmac_f32_e32 v11, s0, v9
	v_cvt_pk_bf16_f32 v9, v11, v11
	v_readlane_b32 s1, v3, 15
	ds_write_b16 v202, v9 offset:3808
	v_readlane_b32 s0, v1, 15
	v_mul_f32_e32 v9, v100, v7
	v_mov_b32_e32 v11, s1
	v_fmac_f32_e32 v11, s0, v9
	v_cvt_pk_bf16_f32 v9, v11, v11
	v_readlane_b32 s1, v3, 16
	ds_write_b16 v202, v9 offset:4080
	v_readlane_b32 s0, v1, 16
	v_mul_f32_e32 v9, v106, v7
	v_mov_b32_e32 v11, s1
	v_fmac_f32_e32 v11, s0, v9
	v_cvt_pk_bf16_f32 v9, v11, v11
	v_readlane_b32 s1, v3, 17
	ds_write_b16 v202, v9 offset:4352
	v_readlane_b32 s0, v1, 17
	v_mul_f32_e32 v9, v102, v7
	v_mov_b32_e32 v11, s1
	v_fmac_f32_e32 v11, s0, v9
	v_cvt_pk_bf16_f32 v9, v11, v11
	v_readlane_b32 s1, v3, 18
	ds_write_b16 v202, v9 offset:4624
	v_readlane_b32 s0, v1, 18
	v_mul_f32_e32 v9, v98, v7
	v_mov_b32_e32 v11, s1
	v_fmac_f32_e32 v11, s0, v9
	v_cvt_pk_bf16_f32 v9, v11, v11
	v_readlane_b32 s1, v3, 19
	ds_write_b16 v202, v9 offset:4896
	v_readlane_b32 s0, v1, 19
	v_mul_f32_e32 v9, v96, v7
	v_mov_b32_e32 v11, s1
	v_fmac_f32_e32 v11, s0, v9
	v_cvt_pk_bf16_f32 v9, v11, v11
	v_readlane_b32 s1, v3, 20
	ds_write_b16 v202, v9 offset:5168
	v_readlane_b32 s0, v1, 20
	v_mul_f32_e32 v9, v94, v7
	v_mov_b32_e32 v11, s1
	v_fmac_f32_e32 v11, s0, v9
	v_cvt_pk_bf16_f32 v9, v11, v11
	v_readlane_b32 s1, v3, 21
	ds_write_b16 v202, v9 offset:5440
	v_readlane_b32 s0, v1, 21
	v_mul_f32_e32 v9, v92, v7
	v_mov_b32_e32 v11, s1
	v_fmac_f32_e32 v11, s0, v9
	v_cvt_pk_bf16_f32 v9, v11, v11
	v_readlane_b32 s1, v3, 22
	ds_write_b16 v202, v9 offset:5712
	v_readlane_b32 s0, v1, 22
	v_mul_f32_e32 v9, v88, v7
	v_mov_b32_e32 v11, s1
	v_fmac_f32_e32 v11, s0, v9
	v_cvt_pk_bf16_f32 v9, v11, v11
	v_readlane_b32 s1, v3, 23
	ds_write_b16 v202, v9 offset:5984
	v_readlane_b32 s0, v1, 23
	v_mul_f32_e32 v9, v84, v7
	v_mov_b32_e32 v11, s1
	v_fmac_f32_e32 v11, s0, v9
	v_cvt_pk_bf16_f32 v9, v11, v11
	v_readlane_b32 s1, v3, 24
	ds_write_b16 v202, v9 offset:6256
	v_readlane_b32 s0, v1, 24
	v_mul_f32_e32 v9, v90, v7
	v_mov_b32_e32 v11, s1
	v_fmac_f32_e32 v11, s0, v9
	v_cvt_pk_bf16_f32 v9, v11, v11
	v_readlane_b32 s1, v3, 25
	ds_write_b16 v202, v9 offset:6528
	v_readlane_b32 s0, v1, 25
	v_mul_f32_e32 v9, v86, v7
	v_mov_b32_e32 v11, s1
	v_fmac_f32_e32 v11, s0, v9
	v_cvt_pk_bf16_f32 v9, v11, v11
	v_readlane_b32 s1, v3, 26
	ds_write_b16 v202, v9 offset:6800
	v_readlane_b32 s0, v1, 26
	v_mul_f32_e32 v9, v82, v7
	v_mov_b32_e32 v11, s1
	v_fmac_f32_e32 v11, s0, v9
	v_cvt_pk_bf16_f32 v9, v11, v11
	v_readlane_b32 s1, v3, 27
	ds_write_b16 v202, v9 offset:7072
	v_readlane_b32 s0, v1, 27
	v_mul_f32_e32 v9, v80, v7
	v_mov_b32_e32 v11, s1
	v_fmac_f32_e32 v11, s0, v9
	v_cvt_pk_bf16_f32 v9, v11, v11
	v_readlane_b32 s1, v3, 28
	ds_write_b16 v202, v9 offset:7344
	v_readlane_b32 s0, v1, 28
	v_mul_f32_e32 v9, v78, v7
	v_mov_b32_e32 v11, s1
	v_fmac_f32_e32 v11, s0, v9
	v_cvt_pk_bf16_f32 v9, v11, v11
	v_readlane_b32 s1, v3, 29
	ds_write_b16 v202, v9 offset:7616
	v_readlane_b32 s0, v1, 29
	v_mul_f32_e32 v9, v76, v7
	v_mov_b32_e32 v11, s1
	v_fmac_f32_e32 v11, s0, v9
	v_cvt_pk_bf16_f32 v9, v11, v11
	v_readlane_b32 s1, v3, 30
	ds_write_b16 v202, v9 offset:7888
	v_readlane_b32 s0, v1, 30
	v_mul_f32_e32 v9, v72, v7
	v_mov_b32_e32 v11, s1
	v_fmac_f32_e32 v11, s0, v9
	v_cvt_pk_bf16_f32 v9, v11, v11
	v_readlane_b32 s1, v3, 31
	ds_write_b16 v202, v9 offset:8160
	v_readlane_b32 s0, v1, 31
	v_mul_f32_e32 v9, v60, v7
	v_mov_b32_e32 v11, s1
	v_fmac_f32_e32 v11, s0, v9
	v_cvt_pk_bf16_f32 v9, v11, v11
	v_readlane_b32 s1, v3, 32
	ds_write_b16 v202, v9 offset:8432
	v_readlane_b32 s0, v1, 32
	v_mul_f32_e32 v9, v74, v7
	v_mov_b32_e32 v11, s1
	v_fmac_f32_e32 v11, s0, v9
	v_cvt_pk_bf16_f32 v9, v11, v11
	v_readlane_b32 s1, v3, 33
	ds_write_b16 v202, v9 offset:8704
	v_readlane_b32 s0, v1, 33
	v_mul_f32_e32 v9, v62, v7
	v_mov_b32_e32 v11, s1
	v_fmac_f32_e32 v11, s0, v9
	v_cvt_pk_bf16_f32 v9, v11, v11
	v_readlane_b32 s1, v3, 34
	ds_write_b16 v202, v9 offset:8976
	v_readlane_b32 s0, v1, 34
	v_mul_f32_e32 v9, v58, v7
	v_mov_b32_e32 v11, s1
	v_fmac_f32_e32 v11, s0, v9
	v_cvt_pk_bf16_f32 v9, v11, v11
	v_readlane_b32 s1, v3, 35
	ds_write_b16 v202, v9 offset:9248
	v_readlane_b32 s0, v1, 35
	v_mul_f32_e32 v9, v56, v7
	v_mov_b32_e32 v11, s1
	v_fmac_f32_e32 v11, s0, v9
	v_cvt_pk_bf16_f32 v9, v11, v11
	v_readlane_b32 s1, v3, 36
	ds_write_b16 v202, v9 offset:9520
	v_readlane_b32 s0, v1, 36
	v_mul_f32_e32 v9, v54, v7
	v_mov_b32_e32 v11, s1
	v_fmac_f32_e32 v11, s0, v9
	v_cvt_pk_bf16_f32 v9, v11, v11
; __device__ __forceinline__ bf16_t f2bf(float f) { return (bf16_t)(cvt_pk_bf16(f, f) & 0xffffu); }
; __device__ __forceinline__ void sg_item(int l, int chunk, LAS unsigned char* lds, const bf16_t* UB, const bf16_t* V2T, bf16_t* YC1, const bf16_t* Wb,
;                                         const float* sg_ln_g, const float* sg_ln_b, const float* sg_b, int lane, int wave) {
;     ...
;         for (int c = 0; c < 64; ++c) {
;             const float gc = __uint_as_float(__builtin_amdgcn_readlane(__float_as_uint(gl), c)), bc = __uint_as_float(__builtin_amdgcn_readlane(__float_as_uint(bl), c));
;             vT[(64 * cq + c) * VS + s] = f2bf((v[c] - mean) * rstd * gc + bc);
;         }
;     }
;     __syncthreads();
	v_readlane_b32 s1, v3, 37
	ds_write_b16 v202, v9 offset:9792
	v_readlane_b32 s0, v1, 37
	v_mul_f32_e32 v9, v52, v7
	v_mov_b32_e32 v11, s1
	v_fmac_f32_e32 v11, s0, v9
	v_cvt_pk_bf16_f32 v9, v11, v11
	v_readlane_b32 s1, v3, 38
	ds_write_b16 v202, v9 offset:10064
	v_readlane_b32 s0, v1, 38
	v_mul_f32_e32 v9, v48, v7
	v_mov_b32_e32 v11, s1
	v_fmac_f32_e32 v11, s0, v9
	v_cvt_pk_bf16_f32 v9, v11, v11
	v_readlane_b32 s1, v3, 39
	ds_write_b16 v202, v9 offset:10336
	v_readlane_b32 s0, v1, 39
	v_mul_f32_e32 v9, v44, v7
	v_mov_b32_e32 v11, s1
	v_fmac_f32_e32 v11, s0, v9
	v_cvt_pk_bf16_f32 v9, v11, v11
	v_readlane_b32 s1, v3, 40
	ds_write_b16 v202, v9 offset:10608
	v_readlane_b32 s0, v1, 40
	v_mul_f32_e32 v9, v50, v7
	v_mov_b32_e32 v11, s1
	v_fmac_f32_e32 v11, s0, v9
	v_cvt_pk_bf16_f32 v9, v11, v11
	v_readlane_b32 s1, v3, 41
	ds_write_b16 v202, v9 offset:10880
	v_readlane_b32 s0, v1, 41
	v_mul_f32_e32 v9, v46, v7
	v_mov_b32_e32 v11, s1
	v_fmac_f32_e32 v11, s0, v9
	v_cvt_pk_bf16_f32 v9, v11, v11
	v_readlane_b32 s1, v3, 42
	ds_write_b16 v202, v9 offset:11152
	v_readlane_b32 s0, v1, 42
	v_mul_f32_e32 v9, v42, v7
	v_mov_b32_e32 v11, s1
	v_fmac_f32_e32 v11, s0, v9
	v_cvt_pk_bf16_f32 v9, v11, v11
	v_readlane_b32 s1, v3, 43
	ds_write_b16 v202, v9 offset:11424
	v_readlane_b32 s0, v1, 43
	v_mul_f32_e32 v9, v40, v7
	v_mov_b32_e32 v11, s1
	v_fmac_f32_e32 v11, s0, v9
	v_cvt_pk_bf16_f32 v9, v11, v11
	v_readlane_b32 s1, v3, 44
	ds_write_b16 v202, v9 offset:11696
	v_readlane_b32 s0, v1, 44
	v_mul_f32_e32 v9, v38, v7
	v_mov_b32_e32 v11, s1
	v_fmac_f32_e32 v11, s0, v9
	v_cvt_pk_bf16_f32 v9, v11, v11
	v_readlane_b32 s1, v3, 45
	ds_write_b16 v202, v9 offset:11968
	v_readlane_b32 s0, v1, 45
	v_mul_f32_e32 v9, v36, v7
	v_mov_b32_e32 v11, s1
	v_fmac_f32_e32 v11, s0, v9
	v_cvt_pk_bf16_f32 v9, v11, v11
	v_readlane_b32 s1, v3, 46
	ds_write_b16 v202, v9 offset:12240
	v_readlane_b32 s0, v1, 46
	v_mul_f32_e32 v9, v32, v7
	v_mov_b32_e32 v11, s1
	v_fmac_f32_e32 v11, s0, v9
	v_cvt_pk_bf16_f32 v9, v11, v11
	v_readlane_b32 s1, v3, 47
	ds_write_b16 v202, v9 offset:12512
	v_readlane_b32 s0, v1, 47
	v_mul_f32_e32 v9, v28, v7
	v_mov_b32_e32 v11, s1
	v_fmac_f32_e32 v11, s0, v9
	v_cvt_pk_bf16_f32 v9, v11, v11
	v_readlane_b32 s1, v3, 48
	ds_write_b16 v202, v9 offset:12784
	v_readlane_b32 s0, v1, 48
	v_mul_f32_e32 v9, v34, v7
	v_mov_b32_e32 v11, s1
	v_fmac_f32_e32 v11, s0, v9
	v_cvt_pk_bf16_f32 v9, v11, v11
	v_readlane_b32 s1, v3, 49
	ds_write_b16 v202, v9 offset:13056
	v_readlane_b32 s0, v1, 49
	v_mul_f32_e32 v9, v30, v7
	v_mov_b32_e32 v11, s1
	v_fmac_f32_e32 v11, s0, v9
	v_cvt_pk_bf16_f32 v9, v11, v11
	v_readlane_b32 s1, v3, 50
	v_fmac_f32_e32 v26, 0xbb800000, v5
	ds_write_b16 v202, v9 offset:13328
	v_readlane_b32 s0, v1, 50
	v_mul_f32_e32 v9, v26, v7
	v_mov_b32_e32 v11, s1
	v_fmac_f32_e32 v11, s0, v9
	v_cvt_pk_bf16_f32 v9, v11, v11
	v_readlane_b32 s1, v3, 51
	v_fmac_f32_e32 v24, 0xbb800000, v5
	ds_write_b16 v202, v9 offset:13600
	v_readlane_b32 s0, v1, 51
	v_mul_f32_e32 v9, v24, v7
	v_mov_b32_e32 v11, s1
	v_fmac_f32_e32 v11, s0, v9
	v_cvt_pk_bf16_f32 v9, v11, v11
	v_readlane_b32 s1, v3, 52
	v_fmac_f32_e32 v22, 0xbb800000, v5
	ds_write_b16 v202, v9 offset:13872
	v_readlane_b32 s0, v1, 52
	v_mul_f32_e32 v9, v22, v7
	v_mov_b32_e32 v11, s1
	v_fmac_f32_e32 v11, s0, v9
	v_cvt_pk_bf16_f32 v9, v11, v11
	v_readlane_b32 s1, v3, 53
	v_fmac_f32_e32 v20, 0xbb800000, v5
	ds_write_b16 v202, v9 offset:14144
	v_readlane_b32 s0, v1, 53
	v_mul_f32_e32 v9, v20, v7
	v_mov_b32_e32 v11, s1
	v_fmac_f32_e32 v11, s0, v9
	v_cvt_pk_bf16_f32 v9, v11, v11
	v_readlane_b32 s1, v3, 54
	v_fmac_f32_e32 v16, 0xbb800000, v5
	ds_write_b16 v202, v9 offset:14416
	v_readlane_b32 s0, v1, 54
	v_mul_f32_e32 v9, v16, v7
	v_mov_b32_e32 v11, s1
	v_fmac_f32_e32 v11, s0, v9
	v_cvt_pk_bf16_f32 v9, v11, v11
	v_readlane_b32 s1, v3, 55
	v_fmac_f32_e32 v12, 0xbb800000, v5
	ds_write_b16 v202, v9 offset:14688
	v_readlane_b32 s0, v1, 55
	v_mul_f32_e32 v9, v12, v7
	v_mov_b32_e32 v11, s1
	v_fmac_f32_e32 v11, s0, v9
	v_cvt_pk_bf16_f32 v9, v11, v11
	v_readlane_b32 s1, v3, 56
	v_fmac_f32_e32 v18, 0xbb800000, v5
	ds_write_b16 v202, v9 offset:14960
	v_readlane_b32 s0, v1, 56
	v_mul_f32_e32 v9, v18, v7
	v_mov_b32_e32 v11, s1
	v_fmac_f32_e32 v11, s0, v9
	v_cvt_pk_bf16_f32 v9, v11, v11
	v_readlane_b32 s1, v3, 57
	v_fmac_f32_e32 v14, 0xbb800000, v5
	ds_write_b16 v202, v9 offset:15232
	v_readlane_b32 s0, v1, 57
	v_mul_f32_e32 v9, v14, v7
	v_mov_b32_e32 v11, s1
	v_fmac_f32_e32 v11, s0, v9
	v_cvt_pk_bf16_f32 v9, v11, v11
	v_readlane_b32 s1, v3, 58
	v_fmac_f32_e32 v10, 0xbb800000, v5
	ds_write_b16 v202, v9 offset:15504
	v_readlane_b32 s0, v1, 58
	v_mul_f32_e32 v9, v10, v7
	v_mov_b32_e32 v10, s1
	v_fmac_f32_e32 v10, s0, v9
	v_cvt_pk_bf16_f32 v9, v10, v10
	v_readlane_b32 s1, v3, 59
	v_fmac_f32_e32 v8, 0xbb800000, v5
	ds_write_b16 v202, v9 offset:15776
	v_readlane_b32 s0, v1, 59
	v_mul_f32_e32 v8, v8, v7
	v_mov_b32_e32 v9, s1
	v_fmac_f32_e32 v9, s0, v8
	v_cvt_pk_bf16_f32 v8, v9, v9
	v_readlane_b32 s1, v3, 60
	v_fmac_f32_e32 v6, 0xbb800000, v5
	ds_write_b16 v202, v8 offset:16048
	v_readlane_b32 s0, v1, 60
	v_mul_f32_e32 v6, v6, v7
	v_mov_b32_e32 v8, s1
	v_fmac_f32_e32 v8, s0, v6
	v_cvt_pk_bf16_f32 v6, v8, v8
	v_readlane_b32 s1, v3, 61
	v_fmac_f32_e32 v4, 0xbb800000, v5
	ds_write_b16 v202, v6 offset:16320
	v_readlane_b32 s0, v1, 61
	v_mul_f32_e32 v4, v4, v7
	v_mov_b32_e32 v6, s1
	v_fmac_f32_e32 v6, s0, v4
	v_cvt_pk_bf16_f32 v4, v6, v6
	v_readlane_b32 s1, v3, 62
	v_fmac_f32_e32 v2, 0xbb800000, v5
	ds_write_b16 v202, v4 offset:16592
	v_readlane_b32 s0, v1, 62
	v_mul_f32_e32 v2, v2, v7
	v_mov_b32_e32 v4, s1
	v_readlane_b32 s1, v3, 63
	v_fmac_f32_e32 v0, 0xbb800000, v5
	v_fmac_f32_e32 v4, s0, v2
	v_readlane_b32 s0, v1, 63
	v_mul_f32_e32 v0, v0, v7
	v_mov_b32_e32 v1, s1
	v_cvt_pk_bf16_f32 v2, v4, v4
	ds_write_b16 v202, v2 offset:16864
	v_fmac_f32_e32 v1, s0, v0
	v_cvt_pk_bf16_f32 v0, v1, v1
	ds_write_b16 v202, v0 offset:17136
	s_waitcnt lgkmcnt(0)
	s_barrier
; #define LAS __attribute__((address_space(3)))
; __device__ __forceinline__ int crow(int r, int hi) { return (r & 3) + 8 * (r >> 2) + 4 * hi; }
; __device__ __forceinline__ void sg_item(int l, int chunk, LAS unsigned char* lds, const bf16_t* UB, const bf16_t* V2T, bf16_t* YC1, const bf16_t* Wb,
;                                         const float* sg_ln_g, const float* sg_ln_b, const float* sg_b, int lane, int wave) {
;     ...
;         const int g = wave & 3, dt = wave >> 2, q = lane & 31, hi = lane >> 5, c = 64 * g + 32 * dt + q;
;         const bf16_t* Wg = Wb + (size_t)g * 128 * 128;
;         const unsigned avoff = (unsigned)(q * 128 + 8 * hi) * 2u;
;         f32x16 acc[4] = {};
;         bf16x8 Bf[8];
; #pragma unroll
;         for (int ks = 0; ks < 8; ++ks) Bf[ks] = *(const LAS bf16x8*)(vT + c * VS + 16 * ks + 8 * hi);
; #pragma unroll
;         for (int i = 0; i < 4; ++i) {
; #pragma unroll
;             for (int kb = 0; kb < 2 * i + 2; kb += 4) {
;                 u32x4 af[4]; const void* pp[4];
; #pragma unroll
;                 for (int j = 0; j < 4; ++j) pp[j] = Wg + (size_t)(32 * i) * 128 + 16 * ((kb + j) < 2 * i + 2 ? (kb + j) : 0);
;                 ld_b128_s4(af, avoff, pp);
; #pragma unroll
;                 for (int j = 0; j < 4; ++j) if (kb + j < 2 * i + 2) acc[i] = __builtin_amdgcn_mfma_f32_32x32x16_bf16(__builtin_bit_cast(bf16x8, af[j]), Bf[kb + j], acc[i], 0, 0, 0);
;             }
;         }
;         const float sb_lo = sg_b[(l * 4 + g) * 128 + lane], sb_hi = sg_b[(l * 4 + g) * 128 + 64 + lane];
;         const unsigned uvoff = (unsigned)(4 * hi * BW + c) * 2u;
; #pragma unroll
;         for (int i = 0; i < 4; ++i) {
;             unsigned uu[16];
; #pragma unroll
;             for (int rb = 0; rb < 16; rb += 8) {
;                 unsigned raw[8]; const void* pp[8];
; #pragma unroll
;                 for (int j = 0; j < 8; ++j) pp[j] = UB + (r0 + 32 * i + crow(rb + j, 0)) * BW;
;                 ld_u16_s8(raw, uvoff, pp);
	s_mov_b32 s94, 0xaaaaaaaa
	s_mov_b32 s95, 0xaaaaaaaa
	v_and_b32_e32 v234, 1, v244
	v_mul_u32_u24_e32 v234, 0x1fe, v234
	ds_read_b128 v[0:3], v201
	ds_read_b128 v[72:75], v201 offset:32
	ds_read_b128 v[76:79], v201 offset:64
	ds_read_b128 v[80:83], v201 offset:96
	ds_read_b128 v[84:87], v201 offset:128
	ds_read_b128 v[88:91], v201 offset:160
	ds_read_b128 v[92:95], v201 offset:192
	ds_read_b128 v[96:99], v201 offset:224
	s_add_u32 s98, s92, s80
	s_addc_u32 s99, s93, s81
	global_load_ushort v112, v152, s[48:49]
	s_add_u32 s98, s98, 0x200
	s_addc_u32 s99, s99, 0
	global_load_ushort v113, v152, s[98:99]
	s_add_u32 s98, s98, 0x200
	s_addc_u32 s99, s99, 0
	global_load_ushort v114, v152, s[98:99]
	s_add_u32 s98, s98, 0x200
	s_addc_u32 s99, s99, 0
	global_load_ushort v115, v152, s[98:99]
	s_add_u32 s98, s98, 0xa00
	s_addc_u32 s99, s99, 0
	global_load_ushort v116, v152, s[98:99]
	s_add_u32 s98, s98, 0x200
	s_addc_u32 s99, s99, 0
	global_load_ushort v117, v152, s[98:99]
	s_add_u32 s98, s98, 0x200
	s_addc_u32 s99, s99, 0
	global_load_ushort v118, v152, s[98:99]
	s_add_u32 s98, s98, 0x200
	s_addc_u32 s99, s99, 0
	global_load_ushort v119, v152, s[98:99]
	s_add_u32 s98, s98, 0xa00
	s_addc_u32 s99, s99, 0
	global_load_ushort v120, v152, s[98:99]
	s_add_u32 s98, s98, 0x200
	s_addc_u32 s99, s99, 0
	global_load_ushort v121, v152, s[98:99]
	s_add_u32 s98, s98, 0x200
	s_addc_u32 s99, s99, 0
	global_load_ushort v122, v152, s[98:99]
	s_add_u32 s98, s98, 0x200
	s_addc_u32 s99, s99, 0
	global_load_ushort v123, v152, s[98:99]
	s_add_u32 s98, s98, 0xa00
	s_addc_u32 s99, s99, 0
	global_load_ushort v124, v152, s[98:99]
	s_add_u32 s98, s98, 0x200
	s_addc_u32 s99, s99, 0
	global_load_ushort v125, v152, s[98:99]
	s_add_u32 s98, s98, 0x200
	s_addc_u32 s99, s99, 0
	global_load_ushort v126, v152, s[98:99]
	s_add_u32 s98, s98, 0x200
	s_addc_u32 s99, s99, 0
	global_load_ushort v127, v152, s[98:99]
	s_add_u32 s98, s98, 0xa00
	s_addc_u32 s99, s99, 0
	global_load_ushort v128, v152, s[98:99]
	s_add_u32 s98, s98, 0x200
	s_addc_u32 s99, s99, 0
	global_load_ushort v129, v152, s[98:99]
	s_add_u32 s98, s98, 0x200
	s_addc_u32 s99, s99, 0
	global_load_ushort v130, v152, s[98:99]
	s_add_u32 s98, s98, 0x200
	s_addc_u32 s99, s99, 0
	global_load_ushort v131, v152, s[98:99]
	s_add_u32 s98, s98, 0xa00
	s_addc_u32 s99, s99, 0
	global_load_ushort v132, v152, s[98:99]
	s_add_u32 s98, s98, 0x200
	s_addc_u32 s99, s99, 0
	global_load_ushort v133, v152, s[98:99]
	s_add_u32 s98, s98, 0x200
	s_addc_u32 s99, s99, 0
	global_load_ushort v220, v152, s[98:99]
	s_add_u32 s98, s98, 0x200
	s_addc_u32 s99, s99, 0
	global_load_ushort v221, v152, s[98:99]
	s_add_u32 s98, s98, 0xa00
	s_addc_u32 s99, s99, 0
	global_load_ushort v222, v152, s[98:99]
	s_add_u32 s98, s98, 0x200
	s_addc_u32 s99, s99, 0
	global_load_ushort v223, v152, s[98:99]
	s_add_u32 s98, s98, 0x200
	s_addc_u32 s99, s99, 0
	global_load_ushort v224, v152, s[98:99]
	s_add_u32 s98, s98, 0x200
	s_addc_u32 s99, s99, 0
	global_load_ushort v225, v152, s[98:99]
	s_add_u32 s98, s98, 0xa00
	s_addc_u32 s99, s99, 0
	global_load_ushort v226, v152, s[98:99]
	s_add_u32 s98, s98, 0x200
	s_addc_u32 s99, s99, 0
	global_load_ushort v227, v152, s[98:99]
	s_add_u32 s98, s98, 0x200
	s_addc_u32 s99, s99, 0
	global_load_ushort v228, v152, s[98:99]
	s_add_u32 s98, s98, 0x200
	s_addc_u32 s99, s99, 0
	global_load_ushort v229, v152, s[98:99]
	s_nop 4
	global_load_dwordx4 v[4:7], v203, s[6:7]
	global_load_dwordx4 v[8:11], v203, s[8:9]
	global_load_dwordx4 v[12:15], v203, s[6:7]
	global_load_dwordx4 v[16:19], v203, s[6:7]
	s_waitcnt vmcnt(0)
	s_add_u32 s0, s92, s80
	s_waitcnt lgkmcnt(7)
	v_mfma_f32_32x32x16_bf16 v[48:63], v[4:7], v[0:3], 0
	s_addc_u32 s1, s93, s81
	s_add_u32 s50, s0, 0x200
	s_addc_u32 s51, s1, 0
	s_add_u32 s52, s0, 0x400
	s_addc_u32 s53, s1, 0
	s_add_u32 s54, s0, 0x600
	s_addc_u32 s55, s1, 0
	s_waitcnt lgkmcnt(6)
	v_mfma_f32_32x32x16_bf16 v[48:63], v[8:11], v[72:75], v[48:63]
	s_nop 4
	global_load_dwordx4 v[4:7], v203, s[10:11]
	global_load_dwordx4 v[8:11], v203, s[16:17]
	global_load_dwordx4 v[12:15], v203, s[18:19]
	global_load_dwordx4 v[16:19], v203, s[20:21]
	s_waitcnt vmcnt(0)
	s_add_u32 s56, s0, 0x1000
	s_addc_u32 s57, s1, 0
	s_add_u32 s58, s0, 0x1200
	s_addc_u32 s59, s1, 0
	s_add_u32 s60, s0, 0x1400
	s_addc_u32 s61, s1, 0
	v_mfma_f32_32x32x16_bf16 v[32:47], v[4:7], v[0:3], 0
	s_add_u32 s62, s0, 0x1600
	s_addc_u32 s63, s1, 0
	v_mfma_f32_32x32x16_bf16 v[32:47], v[8:11], v[72:75], v[32:47]
	s_waitcnt lgkmcnt(5)
	v_mfma_f32_32x32x16_bf16 v[32:47], v[12:15], v[76:79], v[32:47]
	s_nop 4
	global_load_dwordx4 v[4:7], v203, s[22:23]
	global_load_dwordx4 v[8:11], v203, s[24:25]
	global_load_dwordx4 v[12:15], v203, s[26:27]
	global_load_dwordx4 v[100:103], v203, s[28:29]
	s_waitcnt vmcnt(0)
	s_waitcnt lgkmcnt(4)
	v_mfma_f32_32x32x16_bf16 v[32:47], v[16:19], v[80:83], v[32:47]
	v_mfma_f32_32x32x16_bf16 v[16:31], v[4:7], v[0:3], 0
	v_mfma_f32_32x32x16_bf16 v[16:31], v[8:11], v[72:75], v[16:31]
	v_mfma_f32_32x32x16_bf16 v[16:31], v[12:15], v[76:79], v[16:31]
	v_mfma_f32_32x32x16_bf16 v[16:31], v[100:103], v[80:83], v[16:31]
	s_nop 4
	global_load_dwordx4 v[4:7], v203, s[30:31]
	global_load_dwordx4 v[8:11], v203, s[34:35]
	global_load_dwordx4 v[12:15], v203, s[22:23]
	global_load_dwordx4 v[100:103], v203, s[22:23]
	s_waitcnt vmcnt(0)
	s_waitcnt lgkmcnt(3)
	v_mfma_f32_32x32x16_bf16 v[16:31], v[4:7], v[84:87], v[16:31]
	s_nop 4
	global_load_dwordx4 v[4:7], v203, s[36:37]
	global_load_dwordx4 v[100:103], v203, s[38:39]
	global_load_dwordx4 v[104:107], v203, s[68:69]
	global_load_dwordx4 v[108:111], v203, s[70:71]
	s_waitcnt vmcnt(0)
	s_waitcnt lgkmcnt(2)
; __device__ __forceinline__ bf16_t f2bf(float f) { return (bf16_t)(cvt_pk_bf16(f, f) & 0xffffu); }
; __device__ __forceinline__ int crow(int r, int hi) { return (r & 3) + 8 * (r >> 2) + 4 * hi; }
; __device__ __forceinline__ void sg_item(int l, int chunk, LAS unsigned char* lds, const bf16_t* UB, const bf16_t* V2T, bf16_t* YC1, const bf16_t* Wb,
;                                         const float* sg_ln_g, const float* sg_ln_b, const float* sg_b, int lane, int wave) {
;     ...
;                 ld_b128_s4(af, avoff, pp);
; #pragma unroll
;                 for (int j = 0; j < 4; ++j) if (kb + j < 2 * i + 2) acc[i] = __builtin_amdgcn_mfma_f32_32x32x16_bf16(__builtin_bit_cast(bf16x8, af[j]), Bf[kb + j], acc[i], 0, 0, 0);
;             }
;         }
;         const float sb_lo = sg_b[(l * 4 + g) * 128 + lane], sb_hi = sg_b[(l * 4 + g) * 128 + 64 + lane];
;         const unsigned uvoff = (unsigned)(4 * hi * BW + c) * 2u;
; #pragma unroll
;         for (int i = 0; i < 4; ++i) {
;             unsigned uu[16];
; #pragma unroll
;             for (int rb = 0; rb < 16; rb += 8) {
;                 unsigned raw[8]; const void* pp[8];
; #pragma unroll
;                 for (int j = 0; j < 8; ++j) pp[j] = UB + (r0 + 32 * i + crow(rb + j, 0)) * BW;
;                 ld_u16_s8(raw, uvoff, pp);
; #pragma unroll
;                 for (int j = 0; j < 8; ++j) uu[rb + j] = raw[j];
;             }
; #pragma unroll
;             for (int r = 0; r < 16; ++r) {
;                 const int t = 32 * i + crow(r, hi);
;                 const float sbv = __int_as_float(__builtin_amdgcn_ds_bpermute((t & 63) << 2, __float_as_int(i < 2 ? sb_lo : sb_hi)));
;                 YC1[(r0 + t) * BW + c] = f2bf(__uint_as_float(uu[r] << 16) * (acc[i][r] + sbv));
;             }
;         }
	v_mfma_f32_32x32x16_bf16 v[16:31], v[8:11], v[88:91], v[16:31]
	v_mfma_f32_32x32x16_bf16 v[0:15], v[4:7], v[0:3], 0
	v_mfma_f32_32x32x16_bf16 v[0:15], v[100:103], v[72:75], v[0:15]
	v_mfma_f32_32x32x16_bf16 v[0:15], v[104:107], v[76:79], v[0:15]
	v_mfma_f32_32x32x16_bf16 v[0:15], v[108:111], v[80:83], v[0:15]
	s_nop 4
	global_load_dwordx4 v[72:75], v203, s[72:73]
	global_load_dwordx4 v[76:79], v203, s[74:75]
	global_load_dwordx4 v[80:83], v203, s[76:77]
	global_load_dwordx4 v[100:103], v203, s[78:79]
	s_waitcnt vmcnt(0)
	s_nop 0
	v_mfma_f32_32x32x16_bf16 v[0:15], v[72:75], v[84:87], v[0:15]
	global_load_dword v75, v[68:69], off
	global_load_dword v74, v[68:69], off offset:256
	s_waitcnt vmcnt(1)
	ds_bpermute_b32 v73, v200, v75
	v_mfma_f32_32x32x16_bf16 v[0:15], v[76:79], v[88:91], v[0:15]
	s_waitcnt lgkmcnt(0)
	v_add_f32_e32 v48, v48, v73
	v_mfma_f32_32x32x16_bf16 v[0:15], v[80:83], v[92:95], v[0:15]
	s_waitcnt vmcnt(0)
	v_mov_b32_e32 v72, v112
	v_mov_b32_e32 v90, v113
	v_mov_b32_e32 v89, v114
	v_mov_b32_e32 v88, v115
	v_mov_b32_e32 v87, v116
	v_mov_b32_e32 v86, v117
	v_mov_b32_e32 v84, v118
	v_mov_b32_e32 v83, v119
	s_add_u32 s48, s0, 0x2000
	s_addc_u32 s49, s1, 0
	s_add_u32 s50, s0, 0x2200
	s_addc_u32 s51, s1, 0
	s_add_u32 s52, s0, 0x2400
	s_addc_u32 s53, s1, 0
	s_add_u32 s54, s0, 0x2600
	s_addc_u32 s55, s1, 0
	s_add_u32 s56, s0, 0x3000
	s_addc_u32 s57, s1, 0
	s_add_u32 s58, s0, 0x3200
	v_lshlrev_b32_e32 v72, 16, v72
	s_addc_u32 s59, s1, 0
	v_mul_f32_e32 v48, v48, v72
	v_lshl_add_u64 v[72:73], v[70:71], 0, s[80:81]
	s_add_u32 s60, s0, 0x3400
	v_add_co_u32_e32 v92, vcc, s12, v72
	s_addc_u32 s61, s1, 0
	s_nop 0
	v_addc_co_u32_e32 v93, vcc, 0, v73, vcc
	s_mov_b32 s12, 0xb401000
	s_add_u32 s62, s0, 0x3600
	v_add_co_u32_e32 v94, vcc, s12, v72
	s_addc_u32 s63, s1, 0
	s_waitcnt vmcnt(0)
	v_mov_b32_e32 v85, v120
	v_mov_b32_e32 v82, v121
	v_mov_b32_e32 v81, v122
	v_mov_b32_e32 v80, v123
	v_mov_b32_e32 v79, v124
	v_mov_b32_e32 v78, v125
	v_mov_b32_e32 v77, v126
	v_mov_b32_e32 v76, v127
	s_add_u32 s98, s98, 0xa00
	s_addc_u32 s99, s99, 0
	global_load_ushort v112, v152, s[98:99]
	s_add_u32 s98, s98, 0x200
	s_addc_u32 s99, s99, 0
	global_load_ushort v113, v152, s[98:99]
	s_add_u32 s98, s98, 0x200
	s_addc_u32 s99, s99, 0
	global_load_ushort v114, v152, s[98:99]
	s_add_u32 s98, s98, 0x200
	s_addc_u32 s99, s99, 0
	global_load_ushort v115, v152, s[98:99]
	s_add_u32 s98, s98, 0xa00
	s_addc_u32 s99, s99, 0
	global_load_ushort v116, v152, s[98:99]
	s_add_u32 s98, s98, 0x200
	s_addc_u32 s99, s99, 0
	global_load_ushort v117, v152, s[98:99]
	s_add_u32 s98, s98, 0x200
	s_addc_u32 s99, s99, 0
	global_load_ushort v118, v152, s[98:99]
	s_add_u32 s98, s98, 0x200
	s_addc_u32 s99, s99, 0
	global_load_ushort v119, v152, s[98:99]
	s_add_u32 s98, s98, 0xa00
	s_addc_u32 s99, s99, 0
	global_load_ushort v120, v152, s[98:99]
	s_add_u32 s98, s98, 0x200
	s_addc_u32 s99, s99, 0
	global_load_ushort v121, v152, s[98:99]
	s_add_u32 s98, s98, 0x200
	s_addc_u32 s99, s99, 0
	global_load_ushort v122, v152, s[98:99]
	s_add_u32 s98, s98, 0x200
	s_addc_u32 s99, s99, 0
	global_load_ushort v123, v152, s[98:99]
	s_add_u32 s98, s98, 0xa00
	s_addc_u32 s99, s99, 0
	global_load_ushort v124, v152, s[98:99]
	s_add_u32 s98, s98, 0x200
	s_addc_u32 s99, s99, 0
	global_load_ushort v125, v152, s[98:99]
	s_add_u32 s98, s98, 0x200
	s_addc_u32 s99, s99, 0
	global_load_ushort v126, v152, s[98:99]
	s_add_u32 s98, s98, 0x200
	s_addc_u32 s99, s99, 0
	global_load_ushort v127, v152, s[98:99]
	v_mov_b32_e32 v232, v48
	s_nop 0
	v_addc_co_u32_e32 v95, vcc, 0, v73, vcc
	ds_bpermute_b32 v48, v204, v75
	v_lshlrev_b32_e32 v90, 16, v90
	s_mov_b32 s12, 0xb402000
	s_add_u32 s48, s0, 0x4000
	s_addc_u32 s49, s1, 0
	s_waitcnt lgkmcnt(0)
	v_add_f32_e32 v48, v49, v48
	v_mul_f32_e32 v48, v48, v90
	v_mov_b32_dpp v233, v232 quad_perm:[1,0,3,2] row_mask:0xf bank_mask:0xf
	v_cndmask_b32_e64 v233, v233, v48, s[94:95]
	v_mov_b32_dpp v231, v48 quad_perm:[1,0,3,2] row_mask:0xf bank_mask:0xf
	v_cndmask_b32_e64 v232, v232, v231, s[94:95]
	v_cvt_pk_bf16_f32 v232, v232, v233
	v_lshl_add_u64 v[230:231], v[92:93], 0, v[234:235]
	global_store_dword v[230:231], v232, off
	ds_bpermute_b32 v48, v205, v75
	v_lshlrev_b32_e32 v49, 16, v89
	s_add_u32 s50, s0, 0x4200
	s_addc_u32 s51, s1, 0
	s_add_u32 s52, s0, 0x4400
	s_waitcnt lgkmcnt(0)
	v_add_f32_e32 v48, v50, v48
	v_mul_f32_e32 v48, v48, v49
	v_mov_b32_e32 v232, v48
	ds_bpermute_b32 v48, v206, v75
	v_lshlrev_b32_e32 v49, 16, v88
	s_addc_u32 s53, s1, 0
	s_add_u32 s54, s0, 0x4600
	s_addc_u32 s55, s1, 0
	s_waitcnt lgkmcnt(0)
	v_add_f32_e32 v48, v51, v48
	v_mul_f32_e32 v48, v48, v49
	v_mov_b32_dpp v233, v232 quad_perm:[1,0,3,2] row_mask:0xf bank_mask:0xf
	v_cndmask_b32_e64 v233, v233, v48, s[94:95]
	v_mov_b32_dpp v231, v48 quad_perm:[1,0,3,2] row_mask:0xf bank_mask:0xf
	v_cndmask_b32_e64 v232, v232, v231, s[94:95]
	v_cvt_pk_bf16_f32 v232, v232, v233
	v_lshl_add_u64 v[230:231], v[92:93], 0, v[234:235]
	global_store_dword v[230:231], v232, off offset:1024
	ds_bpermute_b32 v48, v207, v75
	v_lshlrev_b32_e32 v49, 16, v87
	s_add_u32 s56, s0, 0x5000
	s_addc_u32 s57, s1, 0
	s_add_u32 s58, s0, 0x5200
	s_waitcnt lgkmcnt(0)
	v_add_f32_e32 v48, v52, v48
	v_mul_f32_e32 v48, v48, v49
	v_mov_b32_e32 v232, v48
	ds_bpermute_b32 v48, v208, v75
	v_lshlrev_b32_e32 v49, 16, v86
	s_addc_u32 s59, s1, 0
	s_add_u32 s60, s0, 0x5400
	s_addc_u32 s61, s1, 0
	s_waitcnt lgkmcnt(0)
; __device__ __forceinline__ bf16_t f2bf(float f) { return (bf16_t)(cvt_pk_bf16(f, f) & 0xffffu); }
; __device__ __forceinline__ int crow(int r, int hi) { return (r & 3) + 8 * (r >> 2) + 4 * hi; }
; __device__ __forceinline__ void sg_item(int l, int chunk, LAS unsigned char* lds, const bf16_t* UB, const bf16_t* V2T, bf16_t* YC1, const bf16_t* Wb,
;                                         const float* sg_ln_g, const float* sg_ln_b, const float* sg_b, int lane, int wave) {
;     ...
; #pragma unroll
;         for (int i = 0; i < 4; ++i) {
;             unsigned uu[16];
; #pragma unroll
;             for (int rb = 0; rb < 16; rb += 8) {
;                 unsigned raw[8]; const void* pp[8];
; #pragma unroll
;                 for (int j = 0; j < 8; ++j) pp[j] = UB + (r0 + 32 * i + crow(rb + j, 0)) * BW;
;                 ld_u16_s8(raw, uvoff, pp);
; #pragma unroll
;                 for (int j = 0; j < 8; ++j) uu[rb + j] = raw[j];
;             }
; #pragma unroll
;             for (int r = 0; r < 16; ++r) {
;                 const int t = 32 * i + crow(r, hi);
;                 const float sbv = __int_as_float(__builtin_amdgcn_ds_bpermute((t & 63) << 2, __float_as_int(i < 2 ? sb_lo : sb_hi)));
;                 YC1[(r0 + t) * BW + c] = f2bf(__uint_as_float(uu[r] << 16) * (acc[i][r] + sbv));
;             }
;         }
	v_add_f32_e32 v48, v53, v48
	v_mul_f32_e32 v48, v48, v49
	v_mov_b32_dpp v233, v232 quad_perm:[1,0,3,2] row_mask:0xf bank_mask:0xf
	v_cndmask_b32_e64 v233, v233, v48, s[94:95]
	v_mov_b32_dpp v231, v48 quad_perm:[1,0,3,2] row_mask:0xf bank_mask:0xf
	v_cndmask_b32_e64 v232, v232, v231, s[94:95]
	v_cvt_pk_bf16_f32 v232, v232, v233
	v_lshl_add_u64 v[230:231], v[94:95], 0, v[234:235]
	global_store_dword v[230:231], v232, off
	ds_bpermute_b32 v48, v209, v75
	v_lshlrev_b32_e32 v49, 16, v84
	v_lshlrev_b32_e32 v53, 16, v82
	s_add_u32 s62, s0, 0x5600
	s_addc_u32 s63, s1, 0
	s_waitcnt lgkmcnt(0)
	v_add_f32_e32 v48, v54, v48
	v_mul_f32_e32 v48, v48, v49
	v_mov_b32_e32 v232, v48
	ds_bpermute_b32 v48, v210, v75
	v_lshlrev_b32_e32 v49, 16, v83
	v_mfma_f32_32x32x16_bf16 v[0:15], v[100:103], v[96:99], v[0:15]
	v_lshl_add_u64 v[70:71], v[70:71], 0, s[82:83]
	s_waitcnt lgkmcnt(0)
	v_add_f32_e32 v48, v55, v48
	v_mul_f32_e32 v48, v48, v49
	v_mov_b32_dpp v233, v232 quad_perm:[1,0,3,2] row_mask:0xf bank_mask:0xf
	v_cndmask_b32_e64 v233, v233, v48, s[94:95]
	v_mov_b32_dpp v231, v48 quad_perm:[1,0,3,2] row_mask:0xf bank_mask:0xf
	v_cndmask_b32_e64 v232, v232, v231, s[94:95]
	v_cvt_pk_bf16_f32 v232, v232, v233
	v_lshl_add_u64 v[230:231], v[94:95], 0, v[234:235]
	global_store_dword v[230:231], v232, off offset:1024
	ds_bpermute_b32 v48, v211, v75
	v_lshlrev_b32_e32 v49, 16, v85
	s_waitcnt lgkmcnt(0)
	v_add_f32_e32 v48, v56, v48
	v_mul_f32_e32 v48, v48, v49
	v_mov_b32_e32 v232, v48
	v_add_co_u32_e32 v48, vcc, s12, v72
	s_mov_b32 s12, 0xb403000
	s_nop 0
	v_addc_co_u32_e32 v49, vcc, 0, v73, vcc
	v_add_co_u32_e32 v50, vcc, s12, v72
	s_mov_b32 s12, 0xb404000
	s_nop 0
	v_addc_co_u32_e32 v51, vcc, 0, v73, vcc
	ds_bpermute_b32 v52, v212, v75
	s_waitcnt lgkmcnt(0)
	v_add_f32_e32 v52, v57, v52
	v_mul_f32_e32 v52, v52, v53
	v_mov_b32_dpp v233, v232 quad_perm:[1,0,3,2] row_mask:0xf bank_mask:0xf
	v_cndmask_b32_e64 v233, v233, v52, s[94:95]
	v_mov_b32_dpp v231, v52 quad_perm:[1,0,3,2] row_mask:0xf bank_mask:0xf
	v_cndmask_b32_e64 v232, v232, v231, s[94:95]
	v_cvt_pk_bf16_f32 v232, v232, v233
	v_lshl_add_u64 v[230:231], v[48:49], 0, v[234:235]
	global_store_dword v[230:231], v232, off
	ds_bpermute_b32 v52, v213, v75
	v_lshlrev_b32_e32 v53, 16, v81
	s_waitcnt lgkmcnt(0)
	v_add_f32_e32 v52, v58, v52
	v_mul_f32_e32 v52, v52, v53
	v_mov_b32_e32 v232, v52
	ds_bpermute_b32 v52, v214, v75
	v_lshlrev_b32_e32 v53, 16, v80
	s_waitcnt lgkmcnt(0)
	v_add_f32_e32 v52, v59, v52
	v_mul_f32_e32 v52, v52, v53
	v_mov_b32_dpp v233, v232 quad_perm:[1,0,3,2] row_mask:0xf bank_mask:0xf
	v_cndmask_b32_e64 v233, v233, v52, s[94:95]
	v_mov_b32_dpp v231, v52 quad_perm:[1,0,3,2] row_mask:0xf bank_mask:0xf
	v_cndmask_b32_e64 v232, v232, v231, s[94:95]
	v_cvt_pk_bf16_f32 v232, v232, v233
	v_lshl_add_u64 v[230:231], v[48:49], 0, v[234:235]
	global_store_dword v[230:231], v232, off offset:1024
	ds_bpermute_b32 v48, v215, v75
	v_lshlrev_b32_e32 v49, 16, v79
	s_waitcnt lgkmcnt(0)
	v_add_f32_e32 v48, v60, v48
	v_mul_f32_e32 v48, v48, v49
	v_mov_b32_e32 v232, v48
	ds_bpermute_b32 v48, v216, v75
	v_lshlrev_b32_e32 v49, 16, v78
	s_waitcnt lgkmcnt(0)
	v_add_f32_e32 v48, v61, v48
	v_mul_f32_e32 v48, v48, v49
	v_mov_b32_dpp v233, v232 quad_perm:[1,0,3,2] row_mask:0xf bank_mask:0xf
	v_cndmask_b32_e64 v233, v233, v48, s[94:95]
	v_mov_b32_dpp v231, v48 quad_perm:[1,0,3,2] row_mask:0xf bank_mask:0xf
	v_cndmask_b32_e64 v232, v232, v231, s[94:95]
	v_cvt_pk_bf16_f32 v232, v232, v233
	v_lshl_add_u64 v[230:231], v[50:51], 0, v[234:235]
	global_store_dword v[230:231], v232, off
	ds_bpermute_b32 v48, v217, v75
	v_lshlrev_b32_e32 v49, 16, v77
	s_waitcnt lgkmcnt(0)
	v_add_f32_e32 v48, v62, v48
	v_mul_f32_e32 v48, v48, v49
	v_mov_b32_e32 v232, v48
	ds_bpermute_b32 v48, v218, v75
	v_lshlrev_b32_e32 v49, 16, v76
	ds_bpermute_b32 v76, v153, v75
	s_waitcnt lgkmcnt(1)
	v_add_f32_e32 v48, v63, v48
	v_mul_f32_e32 v48, v48, v49
	v_mov_b32_dpp v233, v232 quad_perm:[1,0,3,2] row_mask:0xf bank_mask:0xf
	v_cndmask_b32_e64 v233, v233, v48, s[94:95]
	v_mov_b32_dpp v231, v48 quad_perm:[1,0,3,2] row_mask:0xf bank_mask:0xf
	v_cndmask_b32_e64 v232, v232, v231, s[94:95]
	v_cvt_pk_bf16_f32 v232, v232, v233
	v_lshl_add_u64 v[230:231], v[50:51], 0, v[234:235]
	global_store_dword v[230:231], v232, off offset:1024
	s_waitcnt vmcnt(63)
	v_mov_b32_e32 v63, v128
	v_mov_b32_e32 v62, v129
	v_mov_b32_e32 v61, v130
	v_mov_b32_e32 v60, v131
	v_mov_b32_e32 v59, v132
	v_mov_b32_e32 v58, v133
	v_mov_b32_e32 v56, v220
	v_mov_b32_e32 v55, v221
	s_add_u32 s48, s0, 0x6000
	s_addc_u32 s49, s1, 0
	s_add_u32 s50, s0, 0x6200
	s_addc_u32 s51, s1, 0
	s_add_u32 s52, s0, 0x6400
	s_addc_u32 s53, s1, 0
	s_add_u32 s54, s0, 0x6600
	s_addc_u32 s55, s1, 0
	s_add_u32 s56, s0, 0x7000
	s_addc_u32 s57, s1, 0
	s_add_u32 s58, s0, 0x7200
	s_addc_u32 s59, s1, 0
	s_add_u32 s60, s0, 0x7400
	s_waitcnt lgkmcnt(0)
	v_add_f32_e32 v32, v32, v76
	v_add_co_u32_e32 v76, vcc, s12, v72
	s_addc_u32 s61, s1, 0
	v_lshlrev_b32_e32 v63, 16, v63
	v_addc_co_u32_e32 v77, vcc, 0, v73, vcc
	s_mov_b32 s12, 0xb405000
	s_add_u32 s62, s0, 0x7600
	v_mul_f32_e32 v32, v32, v63
	v_add_co_u32_e32 v78, vcc, s12, v72
	s_addc_u32 s63, s1, 0
	s_waitcnt vmcnt(58)
; __device__ __forceinline__ bf16_t f2bf(float f) { return (bf16_t)(cvt_pk_bf16(f, f) & 0xffffu); }
; __device__ __forceinline__ int crow(int r, int hi) { return (r & 3) + 8 * (r >> 2) + 4 * hi; }
; __device__ __forceinline__ void sg_item(int l, int chunk, LAS unsigned char* lds, const bf16_t* UB, const bf16_t* V2T, bf16_t* YC1, const bf16_t* Wb,
;                                         const float* sg_ln_g, const float* sg_ln_b, const float* sg_b, int lane, int wave) {
;     ...
; #pragma unroll
;         for (int i = 0; i < 4; ++i) {
;             unsigned uu[16];
; #pragma unroll
;             for (int rb = 0; rb < 16; rb += 8) {
;                 unsigned raw[8]; const void* pp[8];
; #pragma unroll
;                 for (int j = 0; j < 8; ++j) pp[j] = UB + (r0 + 32 * i + crow(rb + j, 0)) * BW;
;                 ld_u16_s8(raw, uvoff, pp);
; #pragma unroll
;                 for (int j = 0; j < 8; ++j) uu[rb + j] = raw[j];
;             }
; #pragma unroll
;             for (int r = 0; r < 16; ++r) {
;                 const int t = 32 * i + crow(r, hi);
;                 const float sbv = __int_as_float(__builtin_amdgcn_ds_bpermute((t & 63) << 2, __float_as_int(i < 2 ? sb_lo : sb_hi)));
;                 YC1[(r0 + t) * BW + c] = f2bf(__uint_as_float(uu[r] << 16) * (acc[i][r] + sbv));
;             }
;         }
	v_mov_b32_e32 v57, v222
	v_mov_b32_e32 v54, v223
	v_mov_b32_e32 v53, v224
	v_mov_b32_e32 v52, v225
	v_mov_b32_e32 v51, v226
	v_mov_b32_e32 v50, v227
	v_mov_b32_e32 v49, v228
	v_mov_b32_e32 v48, v229
	s_add_u32 s98, s98, 0xa00
	s_addc_u32 s99, s99, 0
	global_load_ushort v128, v152, s[98:99]
	s_add_u32 s98, s98, 0x200
	s_addc_u32 s99, s99, 0
	global_load_ushort v129, v152, s[98:99]
	s_add_u32 s98, s98, 0x200
	s_addc_u32 s99, s99, 0
	global_load_ushort v130, v152, s[98:99]
	s_add_u32 s98, s98, 0x200
	s_addc_u32 s99, s99, 0
	global_load_ushort v131, v152, s[98:99]
	s_add_u32 s98, s98, 0xa00
	s_addc_u32 s99, s99, 0
	global_load_ushort v132, v152, s[98:99]
	s_add_u32 s98, s98, 0x200
	s_addc_u32 s99, s99, 0
	global_load_ushort v133, v152, s[98:99]
	s_add_u32 s98, s98, 0x200
	s_addc_u32 s99, s99, 0
	global_load_ushort v220, v152, s[98:99]
	s_add_u32 s98, s98, 0x200
	s_addc_u32 s99, s99, 0
	global_load_ushort v221, v152, s[98:99]
	s_add_u32 s98, s98, 0xa00
	s_addc_u32 s99, s99, 0
	global_load_ushort v222, v152, s[98:99]
	s_add_u32 s98, s98, 0x200
	s_addc_u32 s99, s99, 0
	global_load_ushort v223, v152, s[98:99]
	s_add_u32 s98, s98, 0x200
	s_addc_u32 s99, s99, 0
	global_load_ushort v224, v152, s[98:99]
	s_add_u32 s98, s98, 0x200
	s_addc_u32 s99, s99, 0
	global_load_ushort v225, v152, s[98:99]
	s_add_u32 s98, s98, 0xa00
	s_addc_u32 s99, s99, 0
	global_load_ushort v226, v152, s[98:99]
	s_add_u32 s98, s98, 0x200
	s_addc_u32 s99, s99, 0
	global_load_ushort v227, v152, s[98:99]
	s_add_u32 s98, s98, 0x200
	s_addc_u32 s99, s99, 0
	global_load_ushort v228, v152, s[98:99]
	s_add_u32 s98, s98, 0x200
	s_addc_u32 s99, s99, 0
	global_load_ushort v229, v152, s[98:99]
	v_mov_b32_e32 v232, v32
	s_nop 0
	v_addc_co_u32_e32 v79, vcc, 0, v73, vcc
	ds_bpermute_b32 v32, v154, v75
	v_lshlrev_b32_e32 v62, 16, v62
	s_mov_b32 s12, 0xb406000
	s_add_u32 s48, s0, 0x8000
	s_addc_u32 s49, s1, 0
	s_waitcnt lgkmcnt(0)
	v_add_f32_e32 v32, v33, v32
	v_mul_f32_e32 v32, v32, v62
	v_mov_b32_dpp v233, v232 quad_perm:[1,0,3,2] row_mask:0xf bank_mask:0xf
	v_cndmask_b32_e64 v233, v233, v32, s[94:95]
	v_mov_b32_dpp v231, v32 quad_perm:[1,0,3,2] row_mask:0xf bank_mask:0xf
	v_cndmask_b32_e64 v232, v232, v231, s[94:95]
	v_cvt_pk_bf16_f32 v232, v232, v233
	v_lshl_add_u64 v[230:231], v[76:77], 0, v[234:235]
	global_store_dword v[230:231], v232, off
	ds_bpermute_b32 v32, v155, v75
	v_lshlrev_b32_e32 v33, 16, v61
	s_add_u32 s50, s0, 0x8200
	s_addc_u32 s51, s1, 0
	s_add_u32 s52, s0, 0x8400
	s_waitcnt lgkmcnt(0)
	v_add_f32_e32 v32, v34, v32
	v_mul_f32_e32 v32, v32, v33
	v_mov_b32_e32 v232, v32
	ds_bpermute_b32 v32, v157, v75
	v_lshlrev_b32_e32 v33, 16, v60
	s_addc_u32 s53, s1, 0
	s_add_u32 s54, s0, 0x8600
	s_addc_u32 s55, s1, 0
	s_waitcnt lgkmcnt(0)
	v_add_f32_e32 v32, v35, v32
	v_mul_f32_e32 v32, v32, v33
	v_mov_b32_dpp v233, v232 quad_perm:[1,0,3,2] row_mask:0xf bank_mask:0xf
	v_cndmask_b32_e64 v233, v233, v32, s[94:95]
	v_mov_b32_dpp v231, v32 quad_perm:[1,0,3,2] row_mask:0xf bank_mask:0xf
	v_cndmask_b32_e64 v232, v232, v231, s[94:95]
	v_cvt_pk_bf16_f32 v232, v232, v233
	v_lshl_add_u64 v[230:231], v[76:77], 0, v[234:235]
	global_store_dword v[230:231], v232, off offset:1024
	ds_bpermute_b32 v32, v161, v75
	v_lshlrev_b32_e32 v33, 16, v59
	s_add_u32 s56, s0, 0x9000
	s_addc_u32 s57, s1, 0
	s_add_u32 s58, s0, 0x9200
	s_waitcnt lgkmcnt(0)
	v_add_f32_e32 v32, v36, v32
	v_mul_f32_e32 v32, v32, v33
	v_mov_b32_e32 v232, v32
	ds_bpermute_b32 v32, v162, v75
	v_lshlrev_b32_e32 v33, 16, v58
	s_addc_u32 s59, s1, 0
	s_add_u32 s60, s0, 0x9400
	s_addc_u32 s61, s1, 0
	s_waitcnt lgkmcnt(0)
	v_add_f32_e32 v32, v37, v32
	v_mul_f32_e32 v32, v32, v33
	v_mov_b32_dpp v233, v232 quad_perm:[1,0,3,2] row_mask:0xf bank_mask:0xf
	v_cndmask_b32_e64 v233, v233, v32, s[94:95]
	v_mov_b32_dpp v231, v32 quad_perm:[1,0,3,2] row_mask:0xf bank_mask:0xf
	v_cndmask_b32_e64 v232, v232, v231, s[94:95]
	v_cvt_pk_bf16_f32 v232, v232, v233
	v_lshl_add_u64 v[230:231], v[78:79], 0, v[234:235]
	global_store_dword v[230:231], v232, off
	ds_bpermute_b32 v32, v163, v75
	v_lshlrev_b32_e32 v33, 16, v56
	v_lshlrev_b32_e32 v37, 16, v54
	s_add_u32 s62, s0, 0x9600
	s_addc_u32 s63, s1, 0
	s_waitcnt lgkmcnt(0)
	v_add_f32_e32 v32, v38, v32
	v_mul_f32_e32 v32, v32, v33
	v_mov_b32_e32 v232, v32
	ds_bpermute_b32 v32, v164, v75
	v_lshlrev_b32_e32 v33, 16, v55
	s_waitcnt lgkmcnt(0)
	v_add_f32_e32 v32, v39, v32
	v_mul_f32_e32 v32, v32, v33
	v_mov_b32_dpp v233, v232 quad_perm:[1,0,3,2] row_mask:0xf bank_mask:0xf
	v_cndmask_b32_e64 v233, v233, v32, s[94:95]
	v_mov_b32_dpp v231, v32 quad_perm:[1,0,3,2] row_mask:0xf bank_mask:0xf
	v_cndmask_b32_e64 v232, v232, v231, s[94:95]
	v_cvt_pk_bf16_f32 v232, v232, v233
	v_lshl_add_u64 v[230:231], v[78:79], 0, v[234:235]
	global_store_dword v[230:231], v232, off offset:1024
	ds_bpermute_b32 v32, v165, v75
	v_lshlrev_b32_e32 v33, 16, v57
	s_waitcnt lgkmcnt(0)
	v_add_f32_e32 v32, v40, v32
	v_mul_f32_e32 v32, v32, v33
	v_mov_b32_e32 v232, v32
	v_add_co_u32_e32 v32, vcc, s12, v72
	s_mov_b32 s12, 0xb407000
	s_nop 0
	v_addc_co_u32_e32 v33, vcc, 0, v73, vcc
	v_add_co_u32_e32 v34, vcc, s12, v72
	s_mov_b32 s12, 0xb408000
	s_nop 0
	v_addc_co_u32_e32 v35, vcc, 0, v73, vcc
	ds_bpermute_b32 v36, v166, v75
	s_waitcnt lgkmcnt(0)
	v_add_f32_e32 v36, v41, v36
	v_mul_f32_e32 v36, v36, v37
	v_mov_b32_dpp v233, v232 quad_perm:[1,0,3,2] row_mask:0xf bank_mask:0xf
	v_cndmask_b32_e64 v233, v233, v36, s[94:95]
	v_mov_b32_dpp v231, v36 quad_perm:[1,0,3,2] row_mask:0xf bank_mask:0xf
	v_cndmask_b32_e64 v232, v232, v231, s[94:95]
	v_cvt_pk_bf16_f32 v232, v232, v233
	v_lshl_add_u64 v[230:231], v[32:33], 0, v[234:235]
	global_store_dword v[230:231], v232, off
	ds_bpermute_b32 v36, v167, v75
	v_lshlrev_b32_e32 v37, 16, v53
	s_waitcnt lgkmcnt(0)
; __device__ __forceinline__ bf16_t f2bf(float f) { return (bf16_t)(cvt_pk_bf16(f, f) & 0xffffu); }
; __device__ __forceinline__ int crow(int r, int hi) { return (r & 3) + 8 * (r >> 2) + 4 * hi; }
; __device__ __forceinline__ void sg_item(int l, int chunk, LAS unsigned char* lds, const bf16_t* UB, const bf16_t* V2T, bf16_t* YC1, const bf16_t* Wb,
;                                         const float* sg_ln_g, const float* sg_ln_b, const float* sg_b, int lane, int wave) {
;     ...
; #pragma unroll
;         for (int i = 0; i < 4; ++i) {
;             unsigned uu[16];
; #pragma unroll
;             for (int rb = 0; rb < 16; rb += 8) {
;                 unsigned raw[8]; const void* pp[8];
; #pragma unroll
;                 for (int j = 0; j < 8; ++j) pp[j] = UB + (r0 + 32 * i + crow(rb + j, 0)) * BW;
;                 ld_u16_s8(raw, uvoff, pp);
; #pragma unroll
;                 for (int j = 0; j < 8; ++j) uu[rb + j] = raw[j];
;             }
; #pragma unroll
;             for (int r = 0; r < 16; ++r) {
;                 const int t = 32 * i + crow(r, hi);
;                 const float sbv = __int_as_float(__builtin_amdgcn_ds_bpermute((t & 63) << 2, __float_as_int(i < 2 ? sb_lo : sb_hi)));
;                 YC1[(r0 + t) * BW + c] = f2bf(__uint_as_float(uu[r] << 16) * (acc[i][r] + sbv));
;             }
;         }
	v_add_f32_e32 v36, v42, v36
	v_mul_f32_e32 v36, v36, v37
	v_mov_b32_e32 v232, v36
	ds_bpermute_b32 v36, v168, v75
	v_lshlrev_b32_e32 v37, 16, v52
	s_waitcnt lgkmcnt(0)
	v_add_f32_e32 v36, v43, v36
	v_mul_f32_e32 v36, v36, v37
	v_mov_b32_dpp v233, v232 quad_perm:[1,0,3,2] row_mask:0xf bank_mask:0xf
	v_cndmask_b32_e64 v233, v233, v36, s[94:95]
	v_mov_b32_dpp v231, v36 quad_perm:[1,0,3,2] row_mask:0xf bank_mask:0xf
	v_cndmask_b32_e64 v232, v232, v231, s[94:95]
	v_cvt_pk_bf16_f32 v232, v232, v233
	v_lshl_add_u64 v[230:231], v[32:33], 0, v[234:235]
	global_store_dword v[230:231], v232, off offset:1024
	ds_bpermute_b32 v32, v169, v75
	v_lshlrev_b32_e32 v33, 16, v51
	s_waitcnt lgkmcnt(0)
	v_add_f32_e32 v32, v44, v32
	v_mul_f32_e32 v32, v32, v33
	v_mov_b32_e32 v232, v32
	ds_bpermute_b32 v32, v170, v75
	v_lshlrev_b32_e32 v33, 16, v50
	s_waitcnt lgkmcnt(0)
	v_add_f32_e32 v32, v45, v32
	v_mul_f32_e32 v32, v32, v33
	v_mov_b32_dpp v233, v232 quad_perm:[1,0,3,2] row_mask:0xf bank_mask:0xf
	v_cndmask_b32_e64 v233, v233, v32, s[94:95]
	v_mov_b32_dpp v231, v32 quad_perm:[1,0,3,2] row_mask:0xf bank_mask:0xf
	v_cndmask_b32_e64 v232, v232, v231, s[94:95]
	v_cvt_pk_bf16_f32 v232, v232, v233
	v_lshl_add_u64 v[230:231], v[34:35], 0, v[234:235]
	global_store_dword v[230:231], v232, off
	ds_bpermute_b32 v32, v171, v75
	v_lshlrev_b32_e32 v33, 16, v49
	s_waitcnt lgkmcnt(0)
	v_add_f32_e32 v32, v46, v32
	v_mul_f32_e32 v32, v32, v33
	v_mov_b32_e32 v232, v32
	ds_bpermute_b32 v32, v172, v75
	v_lshlrev_b32_e32 v33, 16, v48
	s_waitcnt vmcnt(31)
	ds_bpermute_b32 v48, v200, v74
	s_waitcnt lgkmcnt(1)
	v_add_f32_e32 v32, v47, v32
	v_mul_f32_e32 v32, v32, v33
	v_mov_b32_dpp v233, v232 quad_perm:[1,0,3,2] row_mask:0xf bank_mask:0xf
	v_cndmask_b32_e64 v233, v233, v32, s[94:95]
	v_mov_b32_dpp v231, v32 quad_perm:[1,0,3,2] row_mask:0xf bank_mask:0xf
	v_cndmask_b32_e64 v232, v232, v231, s[94:95]
	v_cvt_pk_bf16_f32 v232, v232, v233
	v_lshl_add_u64 v[230:231], v[34:35], 0, v[234:235]
	global_store_dword v[230:231], v232, off offset:1024
	s_waitcnt vmcnt(56)
	v_mov_b32_e32 v47, v112
	v_mov_b32_e32 v46, v113
	v_mov_b32_e32 v45, v114
	v_mov_b32_e32 v44, v115
	v_mov_b32_e32 v43, v116
	v_mov_b32_e32 v42, v117
	v_mov_b32_e32 v40, v118
	v_mov_b32_e32 v39, v119
	s_add_u32 s48, s0, 0xa000
	s_addc_u32 s49, s1, 0
	s_add_u32 s50, s0, 0xa200
	s_addc_u32 s51, s1, 0
	s_add_u32 s52, s0, 0xa400
	s_addc_u32 s53, s1, 0
	s_add_u32 s54, s0, 0xa600
	s_addc_u32 s55, s1, 0
	s_add_u32 s56, s0, 0xb000
	s_addc_u32 s57, s1, 0
	s_add_u32 s58, s0, 0xb200
	s_addc_u32 s59, s1, 0
	s_add_u32 s60, s0, 0xb400
	s_waitcnt lgkmcnt(0)
	v_add_f32_e32 v16, v16, v48
	v_add_co_u32_e32 v48, vcc, s12, v72
	s_addc_u32 s61, s1, 0
	v_lshlrev_b32_e32 v47, 16, v47
	v_addc_co_u32_e32 v49, vcc, 0, v73, vcc
	s_mov_b32 s12, 0xb409000
	s_add_u32 s62, s0, 0xb600
	v_mul_f32_e32 v16, v16, v47
	v_add_co_u32_e32 v50, vcc, s12, v72
	s_addc_u32 s63, s1, 0
	s_waitcnt vmcnt(48)
	v_mov_b32_e32 v41, v120
	v_mov_b32_e32 v38, v121
	v_mov_b32_e32 v37, v122
	v_mov_b32_e32 v36, v123
	v_mov_b32_e32 v35, v124
	v_mov_b32_e32 v34, v125
	v_mov_b32_e32 v33, v126
	v_mov_b32_e32 v32, v127
	v_mov_b32_e32 v232, v16
	s_nop 0
	v_addc_co_u32_e32 v51, vcc, 0, v73, vcc
	ds_bpermute_b32 v16, v173, v74
	v_lshlrev_b32_e32 v46, 16, v46
	s_mov_b32 s12, 0xb40a000
	s_add_u32 s48, s0, 0xc000
	s_addc_u32 s49, s1, 0
	s_waitcnt lgkmcnt(0)
	v_add_f32_e32 v16, v17, v16
	v_mul_f32_e32 v16, v16, v46
	v_mov_b32_dpp v233, v232 quad_perm:[1,0,3,2] row_mask:0xf bank_mask:0xf
	v_cndmask_b32_e64 v233, v233, v16, s[94:95]
	v_mov_b32_dpp v231, v16 quad_perm:[1,0,3,2] row_mask:0xf bank_mask:0xf
	v_cndmask_b32_e64 v232, v232, v231, s[94:95]
	v_cvt_pk_bf16_f32 v232, v232, v233
	v_lshl_add_u64 v[230:231], v[48:49], 0, v[234:235]
	global_store_dword v[230:231], v232, off
	ds_bpermute_b32 v16, v174, v74
	v_lshlrev_b32_e32 v17, 16, v45
	s_add_u32 s50, s0, 0xc200
	s_addc_u32 s51, s1, 0
	s_add_u32 s52, s0, 0xc400
	s_waitcnt lgkmcnt(0)
	v_add_f32_e32 v16, v18, v16
	v_mul_f32_e32 v16, v16, v17
	v_mov_b32_e32 v232, v16
	ds_bpermute_b32 v16, v175, v74
	v_lshlrev_b32_e32 v17, 16, v44
	s_addc_u32 s53, s1, 0
	s_add_u32 s54, s0, 0xc600
	s_addc_u32 s55, s1, 0
	s_waitcnt lgkmcnt(0)
	v_add_f32_e32 v16, v19, v16
	v_mul_f32_e32 v16, v16, v17
	v_mov_b32_dpp v233, v232 quad_perm:[1,0,3,2] row_mask:0xf bank_mask:0xf
	v_cndmask_b32_e64 v233, v233, v16, s[94:95]
	v_mov_b32_dpp v231, v16 quad_perm:[1,0,3,2] row_mask:0xf bank_mask:0xf
	v_cndmask_b32_e64 v232, v232, v231, s[94:95]
	v_cvt_pk_bf16_f32 v232, v232, v233
	v_lshl_add_u64 v[230:231], v[48:49], 0, v[234:235]
	global_store_dword v[230:231], v232, off offset:1024
	ds_bpermute_b32 v16, v176, v74
	v_lshlrev_b32_e32 v17, 16, v43
	s_add_u32 s56, s0, 0xd000
	s_addc_u32 s57, s1, 0
	s_add_u32 s58, s0, 0xd200
	s_waitcnt lgkmcnt(0)
	v_add_f32_e32 v16, v20, v16
	v_mul_f32_e32 v16, v16, v17
	v_mov_b32_e32 v232, v16
	ds_bpermute_b32 v16, v177, v74
	v_lshlrev_b32_e32 v17, 16, v42
	s_addc_u32 s59, s1, 0
	s_add_u32 s60, s0, 0xd400
	s_addc_u32 s61, s1, 0
	s_waitcnt lgkmcnt(0)
	v_add_f32_e32 v16, v21, v16
	v_mul_f32_e32 v16, v16, v17
	v_mov_b32_dpp v233, v232 quad_perm:[1,0,3,2] row_mask:0xf bank_mask:0xf
	v_cndmask_b32_e64 v233, v233, v16, s[94:95]
	v_mov_b32_dpp v231, v16 quad_perm:[1,0,3,2] row_mask:0xf bank_mask:0xf
	v_cndmask_b32_e64 v232, v232, v231, s[94:95]
	v_cvt_pk_bf16_f32 v232, v232, v233
	v_lshl_add_u64 v[230:231], v[50:51], 0, v[234:235]
	global_store_dword v[230:231], v232, off
	ds_bpermute_b32 v16, v178, v74
	v_lshlrev_b32_e32 v17, 16, v40
	v_lshlrev_b32_e32 v21, 16, v38
	s_add_u32 s62, s0, 0xd600
	s_addc_u32 s63, s1, 0
	s_waitcnt lgkmcnt(0)
; __device__ __forceinline__ bf16_t f2bf(float f) { return (bf16_t)(cvt_pk_bf16(f, f) & 0xffffu); }
; __device__ __forceinline__ int crow(int r, int hi) { return (r & 3) + 8 * (r >> 2) + 4 * hi; }
; __device__ __forceinline__ void sg_item(int l, int chunk, LAS unsigned char* lds, const bf16_t* UB, const bf16_t* V2T, bf16_t* YC1, const bf16_t* Wb,
;                                         const float* sg_ln_g, const float* sg_ln_b, const float* sg_b, int lane, int wave) {
;     ...
; #pragma unroll
;         for (int i = 0; i < 4; ++i) {
;             unsigned uu[16];
; #pragma unroll
;             for (int rb = 0; rb < 16; rb += 8) {
;                 unsigned raw[8]; const void* pp[8];
; #pragma unroll
;                 for (int j = 0; j < 8; ++j) pp[j] = UB + (r0 + 32 * i + crow(rb + j, 0)) * BW;
;                 ld_u16_s8(raw, uvoff, pp);
; #pragma unroll
;                 for (int j = 0; j < 8; ++j) uu[rb + j] = raw[j];
;             }
; #pragma unroll
;             for (int r = 0; r < 16; ++r) {
;                 const int t = 32 * i + crow(r, hi);
;                 const float sbv = __int_as_float(__builtin_amdgcn_ds_bpermute((t & 63) << 2, __float_as_int(i < 2 ? sb_lo : sb_hi)));
;                 YC1[(r0 + t) * BW + c] = f2bf(__uint_as_float(uu[r] << 16) * (acc[i][r] + sbv));
;             }
;         }
	v_add_f32_e32 v16, v22, v16
	v_mul_f32_e32 v16, v16, v17
	v_mov_b32_e32 v232, v16
	ds_bpermute_b32 v16, v179, v74
	v_lshlrev_b32_e32 v17, 16, v39
	s_waitcnt lgkmcnt(0)
	v_add_f32_e32 v16, v23, v16
	v_mul_f32_e32 v16, v16, v17
	v_mov_b32_dpp v233, v232 quad_perm:[1,0,3,2] row_mask:0xf bank_mask:0xf
	v_cndmask_b32_e64 v233, v233, v16, s[94:95]
	v_mov_b32_dpp v231, v16 quad_perm:[1,0,3,2] row_mask:0xf bank_mask:0xf
	v_cndmask_b32_e64 v232, v232, v231, s[94:95]
	v_cvt_pk_bf16_f32 v232, v232, v233
	v_lshl_add_u64 v[230:231], v[50:51], 0, v[234:235]
	global_store_dword v[230:231], v232, off offset:1024
	ds_bpermute_b32 v16, v180, v74
	v_lshlrev_b32_e32 v17, 16, v41
	s_waitcnt lgkmcnt(0)
	v_add_f32_e32 v16, v24, v16
	v_mul_f32_e32 v16, v16, v17
	v_mov_b32_e32 v232, v16
	v_add_co_u32_e32 v16, vcc, s12, v72
	s_mov_b32 s12, 0xb40b000
	s_nop 0
	v_addc_co_u32_e32 v17, vcc, 0, v73, vcc
	v_add_co_u32_e32 v18, vcc, s12, v72
	s_nop 1
	v_addc_co_u32_e32 v19, vcc, 0, v73, vcc
	ds_bpermute_b32 v20, v181, v74
	s_waitcnt lgkmcnt(0)
	v_add_f32_e32 v20, v25, v20
	v_mul_f32_e32 v20, v20, v21
	v_mov_b32_dpp v233, v232 quad_perm:[1,0,3,2] row_mask:0xf bank_mask:0xf
	v_cndmask_b32_e64 v233, v233, v20, s[94:95]
	v_mov_b32_dpp v231, v20 quad_perm:[1,0,3,2] row_mask:0xf bank_mask:0xf
	v_cndmask_b32_e64 v232, v232, v231, s[94:95]
	v_cvt_pk_bf16_f32 v232, v232, v233
	v_lshl_add_u64 v[230:231], v[16:17], 0, v[234:235]
	global_store_dword v[230:231], v232, off
	ds_bpermute_b32 v20, v182, v74
	v_lshlrev_b32_e32 v21, 16, v37
	s_waitcnt lgkmcnt(0)
	v_add_f32_e32 v20, v26, v20
	v_mul_f32_e32 v20, v20, v21
	v_mov_b32_e32 v232, v20
	ds_bpermute_b32 v20, v183, v74
	v_lshlrev_b32_e32 v21, 16, v36
	s_waitcnt lgkmcnt(0)
	v_add_f32_e32 v20, v27, v20
	v_mul_f32_e32 v20, v20, v21
	v_mov_b32_dpp v233, v232 quad_perm:[1,0,3,2] row_mask:0xf bank_mask:0xf
	v_cndmask_b32_e64 v233, v233, v20, s[94:95]
	v_mov_b32_dpp v231, v20 quad_perm:[1,0,3,2] row_mask:0xf bank_mask:0xf
	v_cndmask_b32_e64 v232, v232, v231, s[94:95]
	v_cvt_pk_bf16_f32 v232, v232, v233
	v_lshl_add_u64 v[230:231], v[16:17], 0, v[234:235]
	global_store_dword v[230:231], v232, off offset:1024
	ds_bpermute_b32 v16, v184, v74
	v_lshlrev_b32_e32 v17, 16, v35
	s_waitcnt lgkmcnt(0)
	v_add_f32_e32 v16, v28, v16
	v_mul_f32_e32 v16, v16, v17
	v_mov_b32_e32 v232, v16
	ds_bpermute_b32 v16, v185, v74
	v_lshlrev_b32_e32 v17, 16, v34
	s_waitcnt lgkmcnt(0)
	v_add_f32_e32 v16, v29, v16
	v_mul_f32_e32 v16, v16, v17
	v_mov_b32_dpp v233, v232 quad_perm:[1,0,3,2] row_mask:0xf bank_mask:0xf
	v_cndmask_b32_e64 v233, v233, v16, s[94:95]
	v_mov_b32_dpp v231, v16 quad_perm:[1,0,3,2] row_mask:0xf bank_mask:0xf
	v_cndmask_b32_e64 v232, v232, v231, s[94:95]
	v_cvt_pk_bf16_f32 v232, v232, v233
	v_lshl_add_u64 v[230:231], v[18:19], 0, v[234:235]
	global_store_dword v[230:231], v232, off
	ds_bpermute_b32 v16, v186, v74
	v_lshlrev_b32_e32 v17, 16, v33
	s_waitcnt lgkmcnt(0)
	v_add_f32_e32 v16, v30, v16
	v_mul_f32_e32 v16, v16, v17
	v_mov_b32_e32 v232, v16
	ds_bpermute_b32 v16, v187, v74
	v_lshlrev_b32_e32 v17, 16, v32
	ds_bpermute_b32 v32, v188, v74
	s_waitcnt lgkmcnt(1)
	v_add_f32_e32 v16, v31, v16
	v_mul_f32_e32 v16, v16, v17
	v_mov_b32_dpp v233, v232 quad_perm:[1,0,3,2] row_mask:0xf bank_mask:0xf
	v_cndmask_b32_e64 v233, v233, v16, s[94:95]
	v_mov_b32_dpp v231, v16 quad_perm:[1,0,3,2] row_mask:0xf bank_mask:0xf
	v_cndmask_b32_e64 v232, v232, v231, s[94:95]
	v_cvt_pk_bf16_f32 v232, v232, v233
	v_lshl_add_u64 v[230:231], v[18:19], 0, v[234:235]
	global_store_dword v[230:231], v232, off offset:1024
	s_waitcnt vmcnt(40)
	v_mov_b32_e32 v31, v128
	v_mov_b32_e32 v30, v129
	v_mov_b32_e32 v29, v130
	v_mov_b32_e32 v28, v131
	v_mov_b32_e32 v27, v132
	v_mov_b32_e32 v26, v133
	v_mov_b32_e32 v24, v220
	v_mov_b32_e32 v23, v221
	s_add_u32 s48, s0, 0xe000
	s_addc_u32 s49, s1, 0
	s_add_u32 s50, s0, 0xe200
	s_addc_u32 s51, s1, 0
	s_add_u32 s52, s0, 0xe400
	s_addc_u32 s53, s1, 0
	s_add_u32 s54, s0, 0xe600
	s_addc_u32 s55, s1, 0
	s_add_u32 s56, s0, 0xf000
	s_addc_u32 s57, s1, 0
	s_add_u32 s58, s0, 0xf200
	s_addc_u32 s59, s1, 0
	s_add_u32 s60, s0, 0xf400
	s_addc_u32 s61, s1, 0
	s_add_u32 s0, s0, 0xf600
	s_addc_u32 s1, s1, 0
	s_waitcnt vmcnt(32)
	v_mov_b32_e32 v25, v222
	v_mov_b32_e32 v22, v223
	v_mov_b32_e32 v21, v224
	v_mov_b32_e32 v20, v225
	v_mov_b32_e32 v19, v226
	v_mov_b32_e32 v18, v227
	v_mov_b32_e32 v17, v228
	v_mov_b32_e32 v16, v229
	s_mov_b32 s0, 0xb40c000
	s_waitcnt lgkmcnt(0)
	v_add_f32_e32 v0, v0, v32
	v_add_co_u32_e32 v32, vcc, s0, v72
	v_lshlrev_b32_e32 v31, 16, v31
	s_nop 0
	v_addc_co_u32_e32 v33, vcc, 0, v73, vcc
	s_mov_b32 s0, 0xb40d000
	v_mul_f32_e32 v0, v0, v31
	v_add_co_u32_e32 v34, vcc, s0, v72
	v_mov_b32_e32 v232, v0
	v_lshlrev_b32_e32 v30, 16, v30
	s_nop 0
	v_addc_co_u32_e32 v35, vcc, 0, v73, vcc
	ds_bpermute_b32 v0, v189, v74
	s_mov_b32 s0, 0xb40e000
	s_add_i32 s13, s13, s96
	s_add_u32 s92, s92, s82
	s_addc_u32 s93, s93, s83
	s_waitcnt lgkmcnt(0)
	v_add_f32_e32 v0, v1, v0
	v_mul_f32_e32 v0, v0, v30
	v_mov_b32_dpp v233, v232 quad_perm:[1,0,3,2] row_mask:0xf bank_mask:0xf
	v_cndmask_b32_e64 v233, v233, v0, s[94:95]
	v_mov_b32_dpp v231, v0 quad_perm:[1,0,3,2] row_mask:0xf bank_mask:0xf
	v_cndmask_b32_e64 v232, v232, v231, s[94:95]
	v_cvt_pk_bf16_f32 v232, v232, v233
	v_lshl_add_u64 v[230:231], v[32:33], 0, v[234:235]
	global_store_dword v[230:231], v232, off
	ds_bpermute_b32 v0, v190, v74
	v_lshlrev_b32_e32 v1, 16, v29
	s_add_u32 s4, s4, s82
	s_addc_u32 s5, s5, s83
	s_add_u32 s84, s84, s86
	s_waitcnt lgkmcnt(0)
; __device__ __forceinline__ bf16_t f2bf(float f) { return (bf16_t)(cvt_pk_bf16(f, f) & 0xffffu); }
; __device__ __forceinline__ int crow(int r, int hi) { return (r & 3) + 8 * (r >> 2) + 4 * hi; }
; __device__ __forceinline__ void sg_item(int l, int chunk, LAS unsigned char* lds, const bf16_t* UB, const bf16_t* V2T, bf16_t* YC1, const bf16_t* Wb,
;                                         const float* sg_ln_g, const float* sg_ln_b, const float* sg_b, int lane, int wave) {
;     ...
; #pragma unroll
;         for (int i = 0; i < 4; ++i) {
;             unsigned uu[16];
; #pragma unroll
;             for (int rb = 0; rb < 16; rb += 8) {
;                 unsigned raw[8]; const void* pp[8];
; #pragma unroll
;                 for (int j = 0; j < 8; ++j) pp[j] = UB + (r0 + 32 * i + crow(rb + j, 0)) * BW;
;                 ld_u16_s8(raw, uvoff, pp);
; #pragma unroll
;                 for (int j = 0; j < 8; ++j) uu[rb + j] = raw[j];
;             }
; #pragma unroll
;             for (int r = 0; r < 16; ++r) {
;                 const int t = 32 * i + crow(r, hi);
;                 const float sbv = __int_as_float(__builtin_amdgcn_ds_bpermute((t & 63) << 2, __float_as_int(i < 2 ? sb_lo : sb_hi)));
;                 YC1[(r0 + t) * BW + c] = f2bf(__uint_as_float(uu[r] << 16) * (acc[i][r] + sbv));
;             }
;         }
;     }
;     __syncthreads();
	v_add_f32_e32 v0, v2, v0
	v_mul_f32_e32 v0, v0, v1
	v_mov_b32_e32 v232, v0
	ds_bpermute_b32 v0, v157, v74
	v_lshlrev_b32_e32 v1, 16, v28
	s_addc_u32 s85, s85, s87
	s_add_u32 s88, s88, s90
	s_addc_u32 s89, s89, s91
	s_waitcnt lgkmcnt(0)
	v_add_f32_e32 v0, v3, v0
	v_mul_f32_e32 v0, v0, v1
	v_mov_b32_dpp v233, v232 quad_perm:[1,0,3,2] row_mask:0xf bank_mask:0xf
	v_cndmask_b32_e64 v233, v233, v0, s[94:95]
	v_mov_b32_dpp v231, v0 quad_perm:[1,0,3,2] row_mask:0xf bank_mask:0xf
	v_cndmask_b32_e64 v232, v232, v231, s[94:95]
	v_cvt_pk_bf16_f32 v232, v232, v233
	v_lshl_add_u64 v[230:231], v[32:33], 0, v[234:235]
	global_store_dword v[230:231], v232, off offset:1024
	ds_bpermute_b32 v0, v191, v74
	v_lshlrev_b32_e32 v1, 16, v27
	v_lshlrev_b32_e32 v3, 16, v22
	s_cmpk_gt_i32 s13, 0xff
	s_waitcnt lgkmcnt(0)
	v_add_f32_e32 v0, v4, v0
	v_mul_f32_e32 v0, v0, v1
	v_mov_b32_e32 v232, v0
	ds_bpermute_b32 v0, v192, v74
	v_lshlrev_b32_e32 v1, 16, v26
	s_waitcnt lgkmcnt(0)
	v_add_f32_e32 v0, v5, v0
	v_mul_f32_e32 v0, v0, v1
	v_mov_b32_dpp v233, v232 quad_perm:[1,0,3,2] row_mask:0xf bank_mask:0xf
	v_cndmask_b32_e64 v233, v233, v0, s[94:95]
	v_mov_b32_dpp v231, v0 quad_perm:[1,0,3,2] row_mask:0xf bank_mask:0xf
	v_cndmask_b32_e64 v232, v232, v231, s[94:95]
	v_cvt_pk_bf16_f32 v232, v232, v233
	v_lshl_add_u64 v[230:231], v[34:35], 0, v[234:235]
	global_store_dword v[230:231], v232, off
	ds_bpermute_b32 v0, v193, v74
	v_lshlrev_b32_e32 v1, 16, v24
	s_waitcnt lgkmcnt(0)
	v_add_f32_e32 v0, v6, v0
	v_mul_f32_e32 v0, v0, v1
	v_mov_b32_e32 v232, v0
	ds_bpermute_b32 v0, v164, v74
	v_lshlrev_b32_e32 v1, 16, v23
	s_waitcnt lgkmcnt(0)
	v_add_f32_e32 v0, v7, v0
	v_mul_f32_e32 v0, v0, v1
	v_mov_b32_dpp v233, v232 quad_perm:[1,0,3,2] row_mask:0xf bank_mask:0xf
	v_cndmask_b32_e64 v233, v233, v0, s[94:95]
	v_mov_b32_dpp v231, v0 quad_perm:[1,0,3,2] row_mask:0xf bank_mask:0xf
	v_cndmask_b32_e64 v232, v232, v231, s[94:95]
	v_cvt_pk_bf16_f32 v232, v232, v233
	v_lshl_add_u64 v[230:231], v[34:35], 0, v[234:235]
	global_store_dword v[230:231], v232, off offset:1024
	ds_bpermute_b32 v0, v194, v74
	v_lshlrev_b32_e32 v1, 16, v25
	s_waitcnt lgkmcnt(0)
	v_add_f32_e32 v0, v8, v0
	v_mul_f32_e32 v0, v0, v1
	v_mov_b32_e32 v232, v0
	v_add_co_u32_e32 v0, vcc, s0, v72
	s_mov_b32 s0, 0xb40f000
	s_nop 0
	v_addc_co_u32_e32 v1, vcc, 0, v73, vcc
	v_add_co_u32_e32 v4, vcc, s0, v72
	s_nop 1
	v_addc_co_u32_e32 v5, vcc, 0, v73, vcc
	ds_bpermute_b32 v2, v195, v74
	s_waitcnt lgkmcnt(0)
	v_add_f32_e32 v2, v9, v2
	v_mul_f32_e32 v2, v2, v3
	v_mov_b32_dpp v233, v232 quad_perm:[1,0,3,2] row_mask:0xf bank_mask:0xf
	v_cndmask_b32_e64 v233, v233, v2, s[94:95]
	v_mov_b32_dpp v231, v2 quad_perm:[1,0,3,2] row_mask:0xf bank_mask:0xf
	v_cndmask_b32_e64 v232, v232, v231, s[94:95]
	v_cvt_pk_bf16_f32 v232, v232, v233
	v_lshl_add_u64 v[230:231], v[0:1], 0, v[234:235]
	global_store_dword v[230:231], v232, off
	ds_bpermute_b32 v2, v196, v74
	v_lshlrev_b32_e32 v3, 16, v21
	s_waitcnt lgkmcnt(0)
	v_add_f32_e32 v2, v10, v2
	v_mul_f32_e32 v2, v2, v3
	v_mov_b32_e32 v232, v2
	ds_bpermute_b32 v2, v168, v74
	v_lshlrev_b32_e32 v3, 16, v20
	s_waitcnt lgkmcnt(0)
	v_add_f32_e32 v2, v11, v2
	v_mul_f32_e32 v2, v2, v3
	v_mov_b32_dpp v233, v232 quad_perm:[1,0,3,2] row_mask:0xf bank_mask:0xf
	v_cndmask_b32_e64 v233, v233, v2, s[94:95]
	v_mov_b32_dpp v231, v2 quad_perm:[1,0,3,2] row_mask:0xf bank_mask:0xf
	v_cndmask_b32_e64 v232, v232, v231, s[94:95]
	v_cvt_pk_bf16_f32 v232, v232, v233
	v_lshl_add_u64 v[230:231], v[0:1], 0, v[234:235]
	global_store_dword v[230:231], v232, off offset:1024
	ds_bpermute_b32 v0, v197, v74
	v_lshlrev_b32_e32 v1, 16, v19
	s_waitcnt lgkmcnt(0)
	v_add_f32_e32 v0, v12, v0
	v_mul_f32_e32 v0, v0, v1
	v_mov_b32_e32 v232, v0
	ds_bpermute_b32 v0, v198, v74
	v_lshlrev_b32_e32 v1, 16, v18
	s_waitcnt lgkmcnt(0)
	v_add_f32_e32 v0, v13, v0
	v_mul_f32_e32 v0, v0, v1
	v_mov_b32_dpp v233, v232 quad_perm:[1,0,3,2] row_mask:0xf bank_mask:0xf
	v_cndmask_b32_e64 v233, v233, v0, s[94:95]
	v_mov_b32_dpp v231, v0 quad_perm:[1,0,3,2] row_mask:0xf bank_mask:0xf
	v_cndmask_b32_e64 v232, v232, v231, s[94:95]
	v_cvt_pk_bf16_f32 v232, v232, v233
	v_lshl_add_u64 v[230:231], v[4:5], 0, v[234:235]
	global_store_dword v[230:231], v232, off
	ds_bpermute_b32 v0, v199, v74
	v_lshlrev_b32_e32 v1, 16, v17
	s_waitcnt lgkmcnt(0)
	v_add_f32_e32 v0, v14, v0
	v_mul_f32_e32 v0, v0, v1
	v_mov_b32_e32 v232, v0
	ds_bpermute_b32 v0, v172, v74
	v_lshlrev_b32_e32 v1, 16, v16
	s_waitcnt lgkmcnt(0)
	v_add_f32_e32 v0, v15, v0
	v_mul_f32_e32 v0, v0, v1
	v_mov_b32_dpp v233, v232 quad_perm:[1,0,3,2] row_mask:0xf bank_mask:0xf
	v_cndmask_b32_e64 v233, v233, v0, s[94:95]
	v_mov_b32_dpp v231, v0 quad_perm:[1,0,3,2] row_mask:0xf bank_mask:0xf
	v_cndmask_b32_e64 v232, v232, v231, s[94:95]
	v_cvt_pk_bf16_f32 v232, v232, v233
	v_lshl_add_u64 v[230:231], v[4:5], 0, v[234:235]
	global_store_dword v[230:231], v232, off offset:1024
	s_waitcnt vmcnt(63) expcnt(7) lgkmcnt(15)
	s_barrier
	s_cbranch_scc0 .LBB0_79
